# attention item epilogue: issue the four z-gate loads together (were load-wait-compute-store x4)
# speedup vs baseline: 1.0269x; 1.0097x over previous
; DI unsigned pack2(float a, float b) { f32x2_t v = {a, b}; bf16x2_t r = __builtin_convertvector(v, bf16x2_t); return __builtin_bit_cast(unsigned, r); }
; DI float bflo(unsigned u) { return __uint_as_float(u << 16); }
; DI float bfhi(unsigned u) { return __uint_as_float(u & 0xffff0000u); }
; DI float siluf_(float x) { return x * __builtin_amdgcn_rcpf(1.f + __expf(-x)); }
; DI void attn_write_staged(const f32x16& o0, const f32x16& o1, bf16_t* og, const bf16_t* z, size_t tok0, int head, int lane, bf16_t* wl) {
;   const int q = lane & 31, h = lane >> 5;
; #pragma unroll
;   for (int dt = 0; dt < 2; ++dt)
; #pragma unroll
;     for (int q4 = 0; q4 < 4; ++q4) {
;       const f32x16& o = dt ? o1 : o0;
;       *(uint2*)(wl + q * 72 + dt * 32 + 8 * q4 + 4 * h) = make_uint2(pack2(o[4 * q4], o[4 * q4 + 1]), pack2(o[4 * q4 + 2], o[4 * q4 + 3]));
;     }
; #pragma unroll
;   for (int k = 0; k < 4; ++k) {
;     const int ci = lane + 64 * k, row = ci >> 3, c8 = ci & 7;
;     const u32x4 ov = *(const u32x4*)(wl + row * 72 + c8 * 8);
;     const size_t off = (tok0 + row) * 1024 + head * 64 + c8 * 8;
;     const u32x4 zv = ldg16(z + off);
;     u32x4 r;
;     r.x = pack2(bflo(ov.x) * siluf_(bflo(zv.x)), bfhi(ov.x) * siluf_(bfhi(zv.x)));
;     r.y = pack2(bflo(ov.y) * siluf_(bflo(zv.y)), bfhi(ov.y) * siluf_(bfhi(zv.y)));
;     r.z = pack2(bflo(ov.z) * siluf_(bflo(zv.z)), bfhi(ov.z) * siluf_(bfhi(zv.z)));
;     r.w = pack2(bflo(ov.w) * siluf_(bflo(zv.w)), bfhi(ov.w) * siluf_(bfhi(zv.w)));
;     *(u32x4*)(og + off) = r;
;   }
; DI void phase_attn_swa(const Params& P, const float* sinks, bf16_t* og, unsigned char* smem, int L, int G) {
;     ...
;     const float il = 1.f / l;
; #pragma unroll
;     for (int q = 0; q < 16; ++q) { o0[q] *= il; o1[q] *= il; }
;     attn_write_staged(o0, o1, og, big + SW_Z, (size_t)b * SEQ + t0, head, lane, (bf16_t*)(smem + 40960) + w * (32 * 72));
.LBB0_337:
	s_mov_b32 s41, s39
	v_lshlrev_b32_e32 v35, 6, v173
	v_lshl_add_u64 v[32:33], v[148:149], 0, s[40:41]
	v_or_b32_e32 v35, v35, v130
	v_or_b32_e32 v36, v32, v132
	v_mov_b32_e32 v37, v33
	v_lshlrev_b64 v[40:41], 11, v[36:37]
	v_lshlrev_b32_e32 v35, 1, v35
	v_or_b32_e32 v40, v40, v35
	v_lshl_add_u64 v[36:37], s[36:37], 0, v[40:41]
	v_mov_b32_e32 v254, 0x4000
	v_mov_b32_e32 v255, 0
	v_lshl_add_u64 v[248:249], v[36:37], 0, v[254:255]
	v_lshl_add_u64 v[250:251], v[248:249], 0, v[254:255]
	v_lshl_add_u64 v[252:253], v[250:251], 0, v[254:255]
	global_load_dwordx4 v[36:39], v[36:37], off
	global_load_dwordx4 v[96:99], v[248:249], off
	global_load_dwordx4 v[100:103], v[250:251], off
	global_load_dwordx4 v[104:107], v[252:253], off
	v_div_scale_f32 v42, s[0:1], v34, v34, 1.0
	v_rcp_f32_e32 v43, v42
	v_div_scale_f32 v44, vcc, 1.0, v34, 1.0
	v_add_u32_e32 v45, 0xa000, v166
	v_fma_f32 v46, -v42, v43, 1.0
	v_fmac_f32_e32 v43, v46, v43
	v_mul_f32_e32 v46, v44, v43
	v_fma_f32 v47, -v42, v46, v44
	v_fmac_f32_e32 v46, v47, v43
	v_fma_f32 v42, -v42, v46, v44
	v_div_fmas_f32 v42, v42, v43, v46
	v_div_fixup_f32 v34, v42, v34, 1.0
	v_pk_mul_f32 v[0:1], v[34:35], v[0:1] op_sel_hi:[0,1]
	v_pk_mul_f32 v[2:3], v[34:35], v[2:3] op_sel_hi:[0,1]
	v_pk_mul_f32 v[4:5], v[34:35], v[4:5] op_sel_hi:[0,1]
	v_pk_mul_f32 v[20:21], v[20:21], v[34:35] op_sel_hi:[1,0]
	v_pk_mul_f32 v[6:7], v[34:35], v[6:7] op_sel_hi:[0,1]
	v_pk_mul_f32 v[22:23], v[22:23], v[34:35] op_sel_hi:[1,0]
	v_pk_mul_f32 v[24:25], v[24:25], v[34:35] op_sel_hi:[1,0]
	v_pk_mul_f32 v[10:11], v[34:35], v[10:11] op_sel_hi:[0,1]
	v_pk_mul_f32 v[26:27], v[26:27], v[34:35] op_sel_hi:[1,0]
	v_pk_mul_f32 v[12:13], v[34:35], v[12:13] op_sel_hi:[0,1]
	v_pk_mul_f32 v[16:17], v[16:17], v[34:35] op_sel_hi:[1,0]
	v_pk_mul_f32 v[18:19], v[18:19], v[34:35] op_sel_hi:[1,0]
	v_pk_mul_f32 v[8:9], v[34:35], v[8:9] op_sel_hi:[0,1]
	v_pk_mul_f32 v[28:29], v[28:29], v[34:35] op_sel_hi:[1,0]
	v_pk_mul_f32 v[14:15], v[34:35], v[14:15] op_sel_hi:[0,1]
	v_pk_mul_f32 v[30:31], v[30:31], v[34:35] op_sel_hi:[1,0]
	v_cvt_pk_bf16_f32 v0, v0, v1
	v_cvt_pk_bf16_f32 v1, v2, v3
	v_cvt_pk_bf16_f32 v2, v4, v5
	v_cvt_pk_bf16_f32 v3, v6, v7
	v_cvt_pk_bf16_f32 v5, v10, v11
	v_cvt_pk_bf16_f32 v6, v12, v13
	v_cvt_pk_bf16_f32 v10, v20, v21
	v_cvt_pk_bf16_f32 v11, v22, v23
	v_cvt_pk_bf16_f32 v12, v24, v25
	v_cvt_pk_bf16_f32 v13, v26, v27
	v_cvt_pk_bf16_f32 v4, v8, v9
	v_cvt_pk_bf16_f32 v7, v14, v15
	v_cvt_pk_bf16_f32 v8, v16, v17
	v_cvt_pk_bf16_f32 v9, v18, v19
	v_cvt_pk_bf16_f32 v14, v28, v29
	v_cvt_pk_bf16_f32 v15, v30, v31
	ds_write2_b64 v45, v[0:1], v[2:3] offset1:2
	ds_write2_b64 v45, v[4:5], v[6:7] offset0:4 offset1:6
	ds_write2_b64 v45, v[8:9], v[10:11] offset0:8 offset1:10
	ds_write2_b64 v45, v[12:13], v[14:15] offset0:12 offset1:14
	ds_read_b128 v[0:3], v167 offset:40960
	ds_read_b128 v[4:7], v167 offset:42112
	s_add_i32 s45, s45, s74
	s_cmpk_gt_i32 s45, 0xfff
	s_waitcnt lgkmcnt(1)
	v_lshlrev_b32_e32 v8, 16, v0
	v_and_b32_e32 v9, 0xffff0000, v0
	v_lshlrev_b32_e32 v0, 16, v1
	v_and_b32_e32 v1, 0xffff0000, v1
	s_waitcnt vmcnt(3)
	v_lshlrev_b32_e32 v10, 16, v36
	v_and_b32_e32 v11, 0xffff0000, v36
	v_lshlrev_b32_e32 v12, 16, v37
	v_and_b32_e32 v13, 0xffff0000, v37
	v_mul_f32_e32 v16, 0xbfb8aa3b, v10
	v_mul_f32_e32 v17, 0xbfb8aa3b, v11
	v_mul_f32_e32 v18, 0xbfb8aa3b, v12
	v_mul_f32_e32 v19, 0xbfb8aa3b, v13
	v_exp_f32_e32 v16, v16
	v_exp_f32_e32 v17, v17
	v_exp_f32_e32 v18, v18
	v_exp_f32_e32 v19, v19
	v_lshlrev_b32_e32 v14, 16, v38
	v_and_b32_e32 v15, 0xffff0000, v38
	v_add_f32_e32 v16, 1.0, v16
	v_add_f32_e32 v17, 1.0, v17
	v_add_f32_e32 v18, 1.0, v18
	v_add_f32_e32 v19, 1.0, v19
	v_mul_f32_e32 v20, 0xbfb8aa3b, v14
	v_mul_f32_e32 v21, 0xbfb8aa3b, v15
	v_rcp_f32_e32 v16, v16
	v_rcp_f32_e32 v17, v17
	v_rcp_f32_e32 v18, v18
	v_rcp_f32_e32 v19, v19
	v_exp_f32_e32 v20, v20
	v_exp_f32_e32 v21, v21
	v_pk_mul_f32 v[10:11], v[16:17], v[10:11]
	v_pk_mul_f32 v[12:13], v[18:19], v[12:13]
	v_add_f32_e32 v20, 1.0, v20
	v_pk_mul_f32 v[8:9], v[10:11], v[8:9]
	v_pk_mul_f32 v[10:11], v[12:13], v[0:1]
	v_add_f32_e32 v1, 1.0, v21
	v_rcp_f32_e32 v20, v20
	v_rcp_f32_e32 v21, v1
	v_lshlrev_b32_e32 v12, 16, v39
	v_cvt_pk_bf16_f32 v0, v8, v9
	v_lshlrev_b32_e32 v8, 16, v2
	v_and_b32_e32 v9, 0xffff0000, v2
	v_and_b32_e32 v13, 0xffff0000, v39
	v_mul_f32_e32 v2, 0xbfb8aa3b, v12
	v_cvt_pk_bf16_f32 v1, v10, v11
	v_pk_mul_f32 v[10:11], v[20:21], v[14:15]
	v_exp_f32_e32 v2, v2
	v_mul_f32_e32 v14, 0xbfb8aa3b, v13
	v_exp_f32_e32 v14, v14
	v_pk_mul_f32 v[8:9], v[10:11], v[8:9]
	v_add_f32_e32 v2, 1.0, v2
	v_rcp_f32_e32 v10, v2
	v_add_f32_e32 v2, 1.0, v14
	v_rcp_f32_e32 v11, v2
	v_cvt_pk_bf16_f32 v2, v8, v9
	v_lshlrev_b32_e32 v8, 16, v3
	v_and_b32_e32 v9, 0xffff0000, v3
	v_pk_mul_f32 v[10:11], v[10:11], v[12:13]
	s_waitcnt lgkmcnt(0)
	v_lshlrev_b32_e32 v12, 16, v4
	v_pk_mul_f32 v[8:9], v[10:11], v[8:9]
	v_or_b32_e32 v10, v32, v136
	v_cvt_pk_bf16_f32 v3, v8, v9
	v_lshl_add_u64 v[8:9], s[94:95], 0, v[40:41]
	global_store_dwordx4 v[8:9], v[0:3], off
	v_mov_b32_e32 v11, v33
	v_and_b32_e32 v13, 0xffff0000, v4
	v_or_b32_e32 v0, v32, v134
	v_mov_b32_e32 v1, v33
	v_lshlrev_b64 v[8:9], 11, v[0:1]
	v_or_b32_e32 v8, v8, v35
	v_lshl_add_u64 v[0:1], s[36:37], 0, v[8:9]
	v_lshlrev_b32_e32 v4, 16, v5
	v_and_b32_e32 v5, 0xffff0000, v5
	v_lshlrev_b32_e32 v14, 16, v6
	v_and_b32_e32 v15, 0xffff0000, v6
	v_lshlrev_b32_e32 v6, 16, v7
	v_and_b32_e32 v7, 0xffff0000, v7
	v_lshlrev_b64 v[10:11], 11, v[10:11]
	v_lshl_add_u64 v[8:9], s[94:95], 0, v[8:9]
	v_or_b32_e32 v10, v10, v35
	v_or_b32_e32 v32, v32, v138
	s_waitcnt vmcnt(3)
; DI unsigned pack2(float a, float b) { f32x2_t v = {a, b}; bf16x2_t r = __builtin_convertvector(v, bf16x2_t); return __builtin_bit_cast(unsigned, r); }
; DI float bflo(unsigned u) { return __uint_as_float(u << 16); }
; DI float bfhi(unsigned u) { return __uint_as_float(u & 0xffff0000u); }
; DI float siluf_(float x) { return x * __builtin_amdgcn_rcpf(1.f + __expf(-x)); }
; DI void attn_write_staged(const f32x16& o0, const f32x16& o1, bf16_t* og, const bf16_t* z, size_t tok0, int head, int lane, bf16_t* wl) {
;     ...
;   for (int k = 0; k < 4; ++k) {
;     const int ci = lane + 64 * k, row = ci >> 3, c8 = ci & 7;
;     const u32x4 ov = *(const u32x4*)(wl + row * 72 + c8 * 8);
;     const size_t off = (tok0 + row) * 1024 + head * 64 + c8 * 8;
;     const u32x4 zv = ldg16(z + off);
;     u32x4 r;
;     r.x = pack2(bflo(ov.x) * siluf_(bflo(zv.x)), bfhi(ov.x) * siluf_(bfhi(zv.x)));
;     r.y = pack2(bflo(ov.y) * siluf_(bflo(zv.y)), bfhi(ov.y) * siluf_(bfhi(zv.y)));
;     r.z = pack2(bflo(ov.z) * siluf_(bflo(zv.z)), bfhi(ov.z) * siluf_(bfhi(zv.z)));
;     r.w = pack2(bflo(ov.w) * siluf_(bflo(zv.w)), bfhi(ov.w) * siluf_(bfhi(zv.w)));
;     *(u32x4*)(og + off) = r;
;   }
	v_mov_b32_e32 v0, v96
	v_mov_b32_e32 v1, v97
	v_mov_b32_e32 v2, v98
	v_mov_b32_e32 v3, v99
	v_lshlrev_b32_e32 v16, 16, v0
	v_and_b32_e32 v17, 0xffff0000, v0
	v_lshlrev_b32_e32 v0, 16, v1
	v_and_b32_e32 v1, 0xffff0000, v1
	v_lshlrev_b32_e32 v18, 16, v2
	v_and_b32_e32 v19, 0xffff0000, v2
	v_lshlrev_b32_e32 v2, 16, v3
	v_and_b32_e32 v3, 0xffff0000, v3
	v_mul_f32_e32 v20, 0xbfb8aa3b, v16
	v_mul_f32_e32 v21, 0xbfb8aa3b, v17
	v_mul_f32_e32 v22, 0xbfb8aa3b, v0
	v_mul_f32_e32 v23, 0xbfb8aa3b, v1
	v_mul_f32_e32 v24, 0xbfb8aa3b, v18
	v_mul_f32_e32 v25, 0xbfb8aa3b, v19
	v_mul_f32_e32 v26, 0xbfb8aa3b, v2
	v_mul_f32_e32 v27, 0xbfb8aa3b, v3
	v_exp_f32_e32 v20, v20
	v_exp_f32_e32 v21, v21
	v_exp_f32_e32 v22, v22
	v_exp_f32_e32 v23, v23
	v_exp_f32_e32 v24, v24
	v_exp_f32_e32 v25, v25
	v_exp_f32_e32 v26, v26
	v_exp_f32_e32 v27, v27
	v_add_f32_e32 v20, 1.0, v20
	v_add_f32_e32 v21, 1.0, v21
	v_add_f32_e32 v22, 1.0, v22
	v_add_f32_e32 v23, 1.0, v23
	v_add_f32_e32 v24, 1.0, v24
	v_add_f32_e32 v25, 1.0, v25
	v_add_f32_e32 v26, 1.0, v26
	v_add_f32_e32 v27, 1.0, v27
	v_rcp_f32_e32 v20, v20
	v_rcp_f32_e32 v21, v21
	v_rcp_f32_e32 v22, v22
	v_rcp_f32_e32 v23, v23
	v_rcp_f32_e32 v24, v24
	v_rcp_f32_e32 v25, v25
	v_rcp_f32_e32 v26, v26
	v_rcp_f32_e32 v27, v27
	v_pk_mul_f32 v[16:17], v[20:21], v[16:17]
	v_pk_mul_f32 v[0:1], v[22:23], v[0:1]
	v_pk_mul_f32 v[18:19], v[24:25], v[18:19]
	v_pk_mul_f32 v[2:3], v[26:27], v[2:3]
	v_pk_mul_f32 v[12:13], v[16:17], v[12:13]
	v_pk_mul_f32 v[4:5], v[0:1], v[4:5]
	v_pk_mul_f32 v[14:15], v[18:19], v[14:15]
	v_pk_mul_f32 v[6:7], v[2:3], v[6:7]
	v_cvt_pk_bf16_f32 v0, v12, v13
	v_cvt_pk_bf16_f32 v1, v4, v5
	v_cvt_pk_bf16_f32 v2, v14, v15
	v_cvt_pk_bf16_f32 v3, v6, v7
	global_store_dwordx4 v[8:9], v[0:3], off
	v_lshlrev_b64 v[12:13], 11, v[32:33]
	ds_read_b128 v[4:7], v167 offset:43264
	v_lshl_add_u64 v[0:1], s[36:37], 0, v[10:11]
	v_lshl_add_u64 v[14:15], s[94:95], 0, v[10:11]
	ds_read_b128 v[8:11], v167 offset:44416
	s_waitcnt lgkmcnt(1)
	v_lshlrev_b32_e32 v18, 16, v4
	v_and_b32_e32 v19, 0xffff0000, v4
	v_lshlrev_b32_e32 v4, 16, v5
	v_and_b32_e32 v5, 0xffff0000, v5
	v_lshlrev_b32_e32 v20, 16, v6
	v_and_b32_e32 v21, 0xffff0000, v6
	v_lshlrev_b32_e32 v6, 16, v7
	v_and_b32_e32 v7, 0xffff0000, v7
	v_or_b32_e32 v12, v12, v35
	v_lshl_add_u64 v[16:17], s[36:37], 0, v[12:13]
	s_waitcnt vmcnt(3)
	v_mov_b32_e32 v0, v100
	v_mov_b32_e32 v1, v101
	v_mov_b32_e32 v2, v102
	v_mov_b32_e32 v3, v103
	v_lshlrev_b32_e32 v22, 16, v0
	v_and_b32_e32 v23, 0xffff0000, v0
	v_lshlrev_b32_e32 v0, 16, v1
	v_and_b32_e32 v1, 0xffff0000, v1
	v_lshlrev_b32_e32 v24, 16, v2
	v_and_b32_e32 v25, 0xffff0000, v2
	v_lshlrev_b32_e32 v2, 16, v3
	v_and_b32_e32 v3, 0xffff0000, v3
	v_mul_f32_e32 v26, 0xbfb8aa3b, v22
	v_mul_f32_e32 v27, 0xbfb8aa3b, v23
	v_mul_f32_e32 v28, 0xbfb8aa3b, v0
	v_mul_f32_e32 v29, 0xbfb8aa3b, v1
	v_mul_f32_e32 v30, 0xbfb8aa3b, v24
	v_mul_f32_e32 v31, 0xbfb8aa3b, v25
	v_mul_f32_e32 v32, 0xbfb8aa3b, v2
	v_mul_f32_e32 v33, 0xbfb8aa3b, v3
	v_exp_f32_e32 v26, v26
	v_exp_f32_e32 v27, v27
	v_exp_f32_e32 v28, v28
	v_exp_f32_e32 v29, v29
	v_exp_f32_e32 v30, v30
	v_exp_f32_e32 v31, v31
	v_exp_f32_e32 v32, v32
	v_exp_f32_e32 v33, v33
	v_add_f32_e32 v26, 1.0, v26
	v_add_f32_e32 v27, 1.0, v27
	v_add_f32_e32 v28, 1.0, v28
	v_add_f32_e32 v29, 1.0, v29
	v_add_f32_e32 v30, 1.0, v30
	v_add_f32_e32 v31, 1.0, v31
	v_add_f32_e32 v32, 1.0, v32
	v_add_f32_e32 v33, 1.0, v33
	v_rcp_f32_e32 v26, v26
	v_rcp_f32_e32 v27, v27
	v_rcp_f32_e32 v28, v28
	v_rcp_f32_e32 v29, v29
	v_rcp_f32_e32 v30, v30
	v_rcp_f32_e32 v31, v31
	v_rcp_f32_e32 v32, v32
	v_rcp_f32_e32 v33, v33
	v_pk_mul_f32 v[22:23], v[26:27], v[22:23]
	v_pk_mul_f32 v[0:1], v[28:29], v[0:1]
	v_pk_mul_f32 v[24:25], v[30:31], v[24:25]
	v_pk_mul_f32 v[2:3], v[32:33], v[2:3]
	v_pk_mul_f32 v[18:19], v[22:23], v[18:19]
	v_pk_mul_f32 v[4:5], v[0:1], v[4:5]
	v_pk_mul_f32 v[20:21], v[24:25], v[20:21]
	v_pk_mul_f32 v[6:7], v[2:3], v[6:7]
	v_cvt_pk_bf16_f32 v0, v18, v19
	v_cvt_pk_bf16_f32 v1, v4, v5
	v_cvt_pk_bf16_f32 v2, v20, v21
	v_cvt_pk_bf16_f32 v3, v6, v7
	global_store_dwordx4 v[14:15], v[0:3], off
	v_lshl_add_u64 v[4:5], s[94:95], 0, v[12:13]
	s_waitcnt lgkmcnt(0)
	v_lshlrev_b32_e32 v6, 16, v8
	v_and_b32_e32 v7, 0xffff0000, v8
	v_lshlrev_b32_e32 v8, 16, v9
	v_and_b32_e32 v9, 0xffff0000, v9
	v_lshlrev_b32_e32 v12, 16, v10
	v_and_b32_e32 v13, 0xffff0000, v10
	v_lshlrev_b32_e32 v10, 16, v11
	v_and_b32_e32 v11, 0xffff0000, v11
	s_waitcnt vmcnt(3)
	v_mov_b32_e32 v0, v104
	v_mov_b32_e32 v1, v105
	v_mov_b32_e32 v2, v106
	v_mov_b32_e32 v3, v107
	v_lshlrev_b32_e32 v14, 16, v0
	v_and_b32_e32 v15, 0xffff0000, v0
	v_lshlrev_b32_e32 v0, 16, v1
	v_and_b32_e32 v1, 0xffff0000, v1
	v_lshlrev_b32_e32 v16, 16, v2
	v_and_b32_e32 v17, 0xffff0000, v2
	v_lshlrev_b32_e32 v2, 16, v3
	v_and_b32_e32 v3, 0xffff0000, v3
	v_mul_f32_e32 v18, 0xbfb8aa3b, v14
	v_mul_f32_e32 v19, 0xbfb8aa3b, v15
	v_mul_f32_e32 v20, 0xbfb8aa3b, v0
	v_mul_f32_e32 v21, 0xbfb8aa3b, v1
	v_mul_f32_e32 v22, 0xbfb8aa3b, v16
	v_mul_f32_e32 v23, 0xbfb8aa3b, v17
	v_mul_f32_e32 v24, 0xbfb8aa3b, v2
	v_mul_f32_e32 v25, 0xbfb8aa3b, v3
	v_exp_f32_e32 v18, v18
	v_exp_f32_e32 v19, v19
	v_exp_f32_e32 v20, v20
	v_exp_f32_e32 v21, v21
	v_exp_f32_e32 v22, v22
	v_exp_f32_e32 v23, v23
	v_exp_f32_e32 v24, v24
	v_exp_f32_e32 v25, v25
	v_add_f32_e32 v18, 1.0, v18
	v_add_f32_e32 v19, 1.0, v19
	v_add_f32_e32 v20, 1.0, v20
	v_add_f32_e32 v21, 1.0, v21
	v_add_f32_e32 v22, 1.0, v22
	v_add_f32_e32 v23, 1.0, v23
	v_add_f32_e32 v24, 1.0, v24
	v_add_f32_e32 v25, 1.0, v25
	v_rcp_f32_e32 v18, v18
	v_rcp_f32_e32 v19, v19
	v_rcp_f32_e32 v20, v20
	v_rcp_f32_e32 v21, v21
	v_rcp_f32_e32 v22, v22
	v_rcp_f32_e32 v23, v23
	v_rcp_f32_e32 v24, v24
	v_rcp_f32_e32 v25, v25
	v_pk_mul_f32 v[14:15], v[18:19], v[14:15]
	v_pk_mul_f32 v[0:1], v[20:21], v[0:1]
	v_pk_mul_f32 v[16:17], v[22:23], v[16:17]
	v_pk_mul_f32 v[2:3], v[24:25], v[2:3]
	v_pk_mul_f32 v[6:7], v[14:15], v[6:7]
	v_pk_mul_f32 v[8:9], v[0:1], v[8:9]
	v_pk_mul_f32 v[12:13], v[16:17], v[12:13]
	v_pk_mul_f32 v[10:11], v[2:3], v[10:11]
	v_cvt_pk_bf16_f32 v0, v6, v7
	v_cvt_pk_bf16_f32 v1, v8, v9
	v_cvt_pk_bf16_f32 v2, v12, v13
	v_cvt_pk_bf16_f32 v3, v10, v11
	global_store_dwordx4 v[4:5], v[0:3], off
	s_cbranch_scc1 .LBB0_352

; DI unsigned pack2(float a, float b) { f32x2_t v = {a, b}; bf16x2_t r = __builtin_convertvector(v, bf16x2_t); return __builtin_bit_cast(unsigned, r); }
; DI float bflo(unsigned u) { return __uint_as_float(u << 16); }
; DI float bfhi(unsigned u) { return __uint_as_float(u & 0xffff0000u); }
; DI float siluf_(float x) { return x * __builtin_amdgcn_rcpf(1.f + __expf(-x)); }
; DI void attn_write_staged(const f32x16& o0, const f32x16& o1, bf16_t* og, const bf16_t* z, size_t tok0, int head, int lane, bf16_t* wl) {
;   const int q = lane & 31, h = lane >> 5;
; #pragma unroll
;   for (int dt = 0; dt < 2; ++dt)
; #pragma unroll
;     for (int q4 = 0; q4 < 4; ++q4) {
;       const f32x16& o = dt ? o1 : o0;
;       *(uint2*)(wl + q * 72 + dt * 32 + 8 * q4 + 4 * h) = make_uint2(pack2(o[4 * q4], o[4 * q4 + 1]), pack2(o[4 * q4 + 2], o[4 * q4 + 3]));
;     }
; #pragma unroll
;   for (int k = 0; k < 4; ++k) {
;     const int ci = lane + 64 * k, row = ci >> 3, c8 = ci & 7;
;     const u32x4 ov = *(const u32x4*)(wl + row * 72 + c8 * 8);
;     const size_t off = (tok0 + row) * 1024 + head * 64 + c8 * 8;
;     const u32x4 zv = ldg16(z + off);
;     u32x4 r;
;     r.x = pack2(bflo(ov.x) * siluf_(bflo(zv.x)), bfhi(ov.x) * siluf_(bfhi(zv.x)));
;     r.y = pack2(bflo(ov.y) * siluf_(bflo(zv.y)), bfhi(ov.y) * siluf_(bfhi(zv.y)));
;     r.z = pack2(bflo(ov.z) * siluf_(bflo(zv.z)), bfhi(ov.z) * siluf_(bfhi(zv.z)));
;     r.w = pack2(bflo(ov.w) * siluf_(bflo(zv.w)), bfhi(ov.w) * siluf_(bfhi(zv.w)));
;     *(u32x4*)(og + off) = r;
;   }
; DI void phase_attn_mla(const Params& P, bf16_t* og, unsigned char* smem, int L, int G) {
;     ...
;     const float il = 1.f / l;
; #pragma unroll
;     for (int q = 0; q < 16; ++q) { o0[q] *= il; o1[q] *= il; }
;     attn_write_staged(o0, o1, og, big + ML_Z, (size_t)b * SEQ + t0, head, lane, (bf16_t*)(smem + 49152) + w * (32 * 72));
.LBB0_771:
	v_ashrrev_i32_e32 v163, 31, v162
	v_lshl_add_u64 v[2:3], s[20:21], 0, v[162:163]
	v_or_b32_e32 v0, s18, v138
	v_or_b32_e32 v4, v2, v146
	v_mov_b32_e32 v5, v3
	v_lshlrev_b64 v[48:49], 11, v[4:5]
	v_lshlrev_b32_e32 v50, 1, v0
	v_or_b32_e32 v48, v48, v50
	v_lshl_add_u64 v[4:5], s[10:11], 0, v[48:49]
	v_mov_b32_e32 v254, 0x4000
	v_mov_b32_e32 v255, 0
	v_lshl_add_u64 v[248:249], v[4:5], 0, v[254:255]
	v_lshl_add_u64 v[250:251], v[248:249], 0, v[254:255]
	v_lshl_add_u64 v[252:253], v[250:251], 0, v[254:255]
	global_load_dwordx4 v[4:7], v[4:5], off
	global_load_dwordx4 v[116:119], v[248:249], off
	global_load_dwordx4 v[120:123], v[250:251], off
	global_load_dwordx4 v[124:127], v[252:253], off
	v_div_scale_f32 v0, s[18:19], v165, v165, 1.0
	v_rcp_f32_e32 v8, v0
	v_div_scale_f32 v9, vcc, 1.0, v165, 1.0
	v_add_u32_e32 v51, 0xc000, v177
	v_fma_f32 v10, -v0, v8, 1.0
	v_fmac_f32_e32 v8, v10, v8
	v_mul_f32_e32 v10, v9, v8
	v_fma_f32 v11, -v0, v10, v9
	v_fmac_f32_e32 v10, v11, v8
	v_fma_f32 v0, -v0, v10, v9
	v_div_fmas_f32 v0, v0, v8, v10
	v_div_fixup_f32 v0, v0, v165, 1.0
	v_pk_mul_f32 v[8:9], v[32:33], v[0:1] op_sel_hi:[1,0]
	v_pk_mul_f32 v[10:11], v[16:17], v[0:1] op_sel_hi:[1,0]
	v_pk_mul_f32 v[12:13], v[34:35], v[0:1] op_sel_hi:[1,0]
	v_pk_mul_f32 v[14:15], v[18:19], v[0:1] op_sel_hi:[1,0]
	v_pk_mul_f32 v[16:17], v[36:37], v[0:1] op_sel_hi:[1,0]
	v_pk_mul_f32 v[18:19], v[20:21], v[0:1] op_sel_hi:[1,0]
	v_pk_mul_f32 v[20:21], v[38:39], v[0:1] op_sel_hi:[1,0]
	v_pk_mul_f32 v[24:25], v[24:25], v[0:1] op_sel_hi:[1,0]
	v_pk_mul_f32 v[26:27], v[26:27], v[0:1] op_sel_hi:[1,0]
	v_pk_mul_f32 v[22:23], v[22:23], v[0:1] op_sel_hi:[1,0]
	v_pk_mul_f32 v[32:33], v[40:41], v[0:1] op_sel_hi:[1,0]
	v_pk_mul_f32 v[34:35], v[42:43], v[0:1] op_sel_hi:[1,0]
	v_pk_mul_f32 v[36:37], v[44:45], v[0:1] op_sel_hi:[1,0]
	v_pk_mul_f32 v[28:29], v[28:29], v[0:1] op_sel_hi:[1,0]
	v_pk_mul_f32 v[38:39], v[46:47], v[0:1] op_sel_hi:[1,0]
	v_pk_mul_f32 v[30:31], v[30:31], v[0:1] op_sel_hi:[1,0]
	v_cvt_pk_bf16_f32 v8, v8, v9
	v_cvt_pk_bf16_f32 v9, v12, v13
	v_cvt_pk_bf16_f32 v12, v16, v17
	v_cvt_pk_bf16_f32 v13, v20, v21
	v_cvt_pk_bf16_f32 v10, v10, v11
	v_cvt_pk_bf16_f32 v11, v14, v15
	v_cvt_pk_bf16_f32 v14, v18, v19
	v_cvt_pk_bf16_f32 v18, v24, v25
	v_cvt_pk_bf16_f32 v19, v26, v27
	v_cvt_pk_bf16_f32 v16, v32, v33
	v_cvt_pk_bf16_f32 v17, v34, v35
	v_cvt_pk_bf16_f32 v20, v36, v37
	v_cvt_pk_bf16_f32 v21, v38, v39
	v_cvt_pk_bf16_f32 v15, v22, v23
	v_cvt_pk_bf16_f32 v22, v28, v29
	v_cvt_pk_bf16_f32 v23, v30, v31
	ds_write2_b64 v51, v[8:9], v[12:13] offset1:2
	ds_write2_b64 v51, v[16:17], v[20:21] offset0:4 offset1:6
	ds_write2_b64 v51, v[10:11], v[14:15] offset0:8 offset1:10
	ds_write2_b64 v51, v[18:19], v[22:23] offset0:12 offset1:14
	ds_read_b128 v[8:11], v181 offset:49152
	ds_read_b128 v[12:15], v181 offset:50304
	s_add_i32 s38, s38, s74
	s_cmpk_gt_i32 s38, 0xfff
	s_waitcnt lgkmcnt(1)
	v_lshlrev_b32_e32 v16, 16, v8
	v_and_b32_e32 v17, 0xffff0000, v8
	v_lshlrev_b32_e32 v8, 16, v9
	v_and_b32_e32 v9, 0xffff0000, v9
	s_waitcnt vmcnt(3)
	v_lshlrev_b32_e32 v18, 16, v4
	v_and_b32_e32 v19, 0xffff0000, v4
	v_lshlrev_b32_e32 v4, 16, v5
	v_and_b32_e32 v5, 0xffff0000, v5
	v_lshlrev_b32_e32 v20, 16, v6
	v_and_b32_e32 v21, 0xffff0000, v6
	v_mul_f32_e32 v0, 0xbfb8aa3b, v18
	v_mul_f32_e32 v6, 0xbfb8aa3b, v19
	v_mul_f32_e32 v22, 0xbfb8aa3b, v4
	v_mul_f32_e32 v23, 0xbfb8aa3b, v5
	v_exp_f32_e32 v0, v0
	v_exp_f32_e32 v6, v6
	v_exp_f32_e32 v22, v22
	v_exp_f32_e32 v23, v23
	v_mul_f32_e32 v24, 0xbfb8aa3b, v20
	v_mul_f32_e32 v25, 0xbfb8aa3b, v21
	v_add_f32_e32 v0, 1.0, v0
	v_add_f32_e32 v6, 1.0, v6
	v_exp_f32_e32 v26, v24
	v_exp_f32_e32 v27, v25
	v_add_f32_e32 v24, 1.0, v22
	v_add_f32_e32 v25, 1.0, v23
	v_rcp_f32_e32 v22, v0
	v_rcp_f32_e32 v23, v6
	v_rcp_f32_e32 v24, v24
	v_rcp_f32_e32 v25, v25
	v_add_f32_e32 v0, 1.0, v26
	v_pk_mul_f32 v[18:19], v[22:23], v[18:19]
	v_rcp_f32_e32 v26, v0
	v_pk_mul_f32 v[16:17], v[18:19], v[16:17]
	v_add_f32_e32 v0, 1.0, v27
	v_lshlrev_b32_e32 v18, 16, v7
	v_pk_mul_f32 v[4:5], v[24:25], v[4:5]
	v_rcp_f32_e32 v27, v0
	v_and_b32_e32 v19, 0xffff0000, v7
	v_mul_f32_e32 v0, 0xbfb8aa3b, v18
	v_pk_mul_f32 v[8:9], v[4:5], v[8:9]
	v_exp_f32_e32 v0, v0
	v_mul_f32_e32 v6, 0xbfb8aa3b, v19
	v_cvt_pk_bf16_f32 v5, v8, v9
	v_lshlrev_b32_e32 v8, 16, v10
	v_and_b32_e32 v9, 0xffff0000, v10
	v_exp_f32_e32 v10, v6
	v_cvt_pk_bf16_f32 v4, v16, v17
	v_pk_mul_f32 v[16:17], v[26:27], v[20:21]
	v_add_f32_e32 v0, 1.0, v0
	v_pk_mul_f32 v[6:7], v[16:17], v[8:9]
	v_rcp_f32_e32 v8, v0
	v_add_f32_e32 v0, 1.0, v10
	v_rcp_f32_e32 v9, v0
	v_lshlrev_b32_e32 v10, 16, v11
	v_and_b32_e32 v11, 0xffff0000, v11
	v_cvt_pk_bf16_f32 v6, v6, v7
	v_pk_mul_f32 v[8:9], v[8:9], v[18:19]
	s_waitcnt lgkmcnt(0)
	v_lshlrev_b32_e32 v18, 16, v14
	v_pk_mul_f32 v[8:9], v[8:9], v[10:11]
	v_or_b32_e32 v10, v2, v150
	v_cvt_pk_bf16_f32 v7, v8, v9
	v_lshl_add_u64 v[8:9], s[94:95], 0, v[48:49]
	global_store_dwordx4 v[8:9], v[4:7], off
	v_mov_b32_e32 v11, v3
	v_lshlrev_b64 v[16:17], 11, v[10:11]
	v_or_b32_e32 v4, v2, v148
	v_mov_b32_e32 v5, v3
	v_lshlrev_b64 v[8:9], 11, v[4:5]
	v_or_b32_e32 v8, v8, v50
	v_lshl_add_u64 v[4:5], s[10:11], 0, v[8:9]
	v_lshlrev_b32_e32 v10, 16, v12
	v_and_b32_e32 v11, 0xffff0000, v12
	v_lshlrev_b32_e32 v12, 16, v13
	v_and_b32_e32 v13, 0xffff0000, v13
	v_and_b32_e32 v19, 0xffff0000, v14
	v_lshlrev_b32_e32 v14, 16, v15
	v_and_b32_e32 v15, 0xffff0000, v15
	v_lshl_add_u64 v[8:9], s[94:95], 0, v[8:9]
	v_or_b32_e32 v16, v16, v50
	v_or_b32_e32 v2, v2, v152
	s_waitcnt vmcnt(3)
; DI unsigned pack2(float a, float b) { f32x2_t v = {a, b}; bf16x2_t r = __builtin_convertvector(v, bf16x2_t); return __builtin_bit_cast(unsigned, r); }
; DI float bflo(unsigned u) { return __uint_as_float(u << 16); }
; DI float bfhi(unsigned u) { return __uint_as_float(u & 0xffff0000u); }
; DI float siluf_(float x) { return x * __builtin_amdgcn_rcpf(1.f + __expf(-x)); }
; DI void attn_write_staged(const f32x16& o0, const f32x16& o1, bf16_t* og, const bf16_t* z, size_t tok0, int head, int lane, bf16_t* wl) {
;     ...
;   for (int k = 0; k < 4; ++k) {
;     const int ci = lane + 64 * k, row = ci >> 3, c8 = ci & 7;
;     const u32x4 ov = *(const u32x4*)(wl + row * 72 + c8 * 8);
;     const size_t off = (tok0 + row) * 1024 + head * 64 + c8 * 8;
;     const u32x4 zv = ldg16(z + off);
;     u32x4 r;
;     r.x = pack2(bflo(ov.x) * siluf_(bflo(zv.x)), bfhi(ov.x) * siluf_(bfhi(zv.x)));
;     r.y = pack2(bflo(ov.y) * siluf_(bflo(zv.y)), bfhi(ov.y) * siluf_(bfhi(zv.y)));
;     r.z = pack2(bflo(ov.z) * siluf_(bflo(zv.z)), bfhi(ov.z) * siluf_(bfhi(zv.z)));
;     r.w = pack2(bflo(ov.w) * siluf_(bflo(zv.w)), bfhi(ov.w) * siluf_(bfhi(zv.w)));
;     *(u32x4*)(og + off) = r;
;   }
	v_mov_b32_e32 v4, v116
	v_mov_b32_e32 v5, v117
	v_mov_b32_e32 v6, v118
	v_mov_b32_e32 v7, v119
	v_lshlrev_b32_e32 v20, 16, v4
	v_and_b32_e32 v21, 0xffff0000, v4
	v_lshlrev_b32_e32 v4, 16, v5
	v_and_b32_e32 v5, 0xffff0000, v5
	v_lshlrev_b32_e32 v22, 16, v6
	v_and_b32_e32 v23, 0xffff0000, v6
	v_lshlrev_b32_e32 v6, 16, v7
	v_and_b32_e32 v7, 0xffff0000, v7
	v_mul_f32_e32 v0, 0xbfb8aa3b, v20
	v_mul_f32_e32 v24, 0xbfb8aa3b, v21
	v_mul_f32_e32 v25, 0xbfb8aa3b, v4
	v_mul_f32_e32 v26, 0xbfb8aa3b, v5
	v_mul_f32_e32 v27, 0xbfb8aa3b, v22
	v_mul_f32_e32 v28, 0xbfb8aa3b, v23
	v_mul_f32_e32 v29, 0xbfb8aa3b, v6
	v_mul_f32_e32 v30, 0xbfb8aa3b, v7
	v_exp_f32_e32 v0, v0
	v_exp_f32_e32 v24, v24
	v_exp_f32_e32 v25, v25
	v_exp_f32_e32 v26, v26
	v_exp_f32_e32 v27, v27
	v_exp_f32_e32 v28, v28
	v_exp_f32_e32 v29, v29
	v_exp_f32_e32 v30, v30
	v_add_f32_e32 v0, 1.0, v0
	v_add_f32_e32 v31, 1.0, v24
	v_add_f32_e32 v32, 1.0, v25
	v_add_f32_e32 v33, 1.0, v26
	v_add_f32_e32 v34, 1.0, v27
	v_add_f32_e32 v35, 1.0, v28
	v_add_f32_e32 v36, 1.0, v29
	v_add_f32_e32 v37, 1.0, v30
	v_rcp_f32_e32 v24, v0
	v_rcp_f32_e32 v25, v31
	v_rcp_f32_e32 v26, v32
	v_rcp_f32_e32 v27, v33
	v_rcp_f32_e32 v28, v34
	v_rcp_f32_e32 v29, v35
	v_rcp_f32_e32 v30, v36
	v_rcp_f32_e32 v31, v37
	v_pk_mul_f32 v[20:21], v[24:25], v[20:21]
	v_pk_mul_f32 v[4:5], v[26:27], v[4:5]
	v_pk_mul_f32 v[22:23], v[28:29], v[22:23]
	v_pk_mul_f32 v[6:7], v[30:31], v[6:7]
	v_pk_mul_f32 v[10:11], v[20:21], v[10:11]
	v_pk_mul_f32 v[12:13], v[4:5], v[12:13]
	v_pk_mul_f32 v[18:19], v[22:23], v[18:19]
	v_pk_mul_f32 v[14:15], v[6:7], v[14:15]
	v_cvt_pk_bf16_f32 v4, v10, v11
	v_cvt_pk_bf16_f32 v5, v12, v13
	v_cvt_pk_bf16_f32 v6, v18, v19
	v_cvt_pk_bf16_f32 v7, v14, v15
	global_store_dwordx4 v[8:9], v[4:7], off
	ds_read_b128 v[8:11], v181 offset:51456
	ds_read_b128 v[12:15], v181 offset:52608
	v_lshl_add_u64 v[4:5], s[10:11], 0, v[16:17]
	v_lshlrev_b64 v[18:19], 11, v[2:3]
	s_waitcnt lgkmcnt(1)
	v_lshlrev_b32_e32 v2, 16, v8
	v_and_b32_e32 v3, 0xffff0000, v8
	v_lshlrev_b32_e32 v8, 16, v9
	v_and_b32_e32 v9, 0xffff0000, v9
	v_lshlrev_b32_e32 v22, 16, v10
	v_and_b32_e32 v23, 0xffff0000, v10
	v_lshlrev_b32_e32 v10, 16, v11
	v_and_b32_e32 v11, 0xffff0000, v11
	v_or_b32_e32 v18, v18, v50
	v_lshl_add_u64 v[16:17], s[94:95], 0, v[16:17]
	v_lshl_add_u64 v[20:21], s[10:11], 0, v[18:19]
	s_waitcnt vmcnt(3)
	v_mov_b32_e32 v4, v120
	v_mov_b32_e32 v5, v121
	v_mov_b32_e32 v6, v122
	v_mov_b32_e32 v7, v123
	v_lshlrev_b32_e32 v24, 16, v4
	v_and_b32_e32 v25, 0xffff0000, v4
	v_lshlrev_b32_e32 v4, 16, v5
	v_and_b32_e32 v5, 0xffff0000, v5
	v_lshlrev_b32_e32 v26, 16, v6
	v_and_b32_e32 v27, 0xffff0000, v6
	v_lshlrev_b32_e32 v6, 16, v7
	v_and_b32_e32 v7, 0xffff0000, v7
	v_mul_f32_e32 v0, 0xbfb8aa3b, v24
	v_mul_f32_e32 v28, 0xbfb8aa3b, v25
	v_mul_f32_e32 v29, 0xbfb8aa3b, v4
	v_mul_f32_e32 v30, 0xbfb8aa3b, v5
	v_mul_f32_e32 v31, 0xbfb8aa3b, v26
	v_mul_f32_e32 v32, 0xbfb8aa3b, v27
	v_mul_f32_e32 v33, 0xbfb8aa3b, v6
	v_mul_f32_e32 v34, 0xbfb8aa3b, v7
	v_exp_f32_e32 v0, v0
	v_exp_f32_e32 v28, v28
	v_exp_f32_e32 v29, v29
	v_exp_f32_e32 v30, v30
	v_exp_f32_e32 v31, v31
	v_exp_f32_e32 v32, v32
	v_exp_f32_e32 v33, v33
	v_exp_f32_e32 v34, v34
	v_add_f32_e32 v0, 1.0, v0
	v_add_f32_e32 v35, 1.0, v28
	v_add_f32_e32 v36, 1.0, v29
	v_add_f32_e32 v37, 1.0, v30
	v_add_f32_e32 v38, 1.0, v31
	v_add_f32_e32 v39, 1.0, v32
	v_add_f32_e32 v40, 1.0, v33
	v_add_f32_e32 v41, 1.0, v34
	v_rcp_f32_e32 v28, v0
	v_rcp_f32_e32 v29, v35
	v_rcp_f32_e32 v30, v36
	v_rcp_f32_e32 v31, v37
	v_rcp_f32_e32 v32, v38
	v_rcp_f32_e32 v33, v39
	v_rcp_f32_e32 v34, v40
	v_rcp_f32_e32 v35, v41
	v_pk_mul_f32 v[24:25], v[28:29], v[24:25]
	v_pk_mul_f32 v[4:5], v[30:31], v[4:5]
	v_pk_mul_f32 v[26:27], v[32:33], v[26:27]
	v_pk_mul_f32 v[6:7], v[34:35], v[6:7]
	v_pk_mul_f32 v[2:3], v[24:25], v[2:3]
	v_pk_mul_f32 v[4:5], v[4:5], v[8:9]
	v_pk_mul_f32 v[8:9], v[26:27], v[22:23]
	v_pk_mul_f32 v[6:7], v[6:7], v[10:11]
	v_cvt_pk_bf16_f32 v2, v2, v3
	v_cvt_pk_bf16_f32 v3, v4, v5
	v_cvt_pk_bf16_f32 v4, v8, v9
	v_cvt_pk_bf16_f32 v5, v6, v7
	global_store_dwordx4 v[16:17], v[2:5], off
	v_lshl_add_u64 v[6:7], s[94:95], 0, v[18:19]
	s_waitcnt lgkmcnt(0)
	v_lshlrev_b32_e32 v8, 16, v12
	v_and_b32_e32 v9, 0xffff0000, v12
	v_lshlrev_b32_e32 v10, 16, v13
	v_and_b32_e32 v11, 0xffff0000, v13
	v_lshlrev_b32_e32 v12, 16, v14
	v_and_b32_e32 v13, 0xffff0000, v14
	v_lshlrev_b32_e32 v14, 16, v15
	v_and_b32_e32 v15, 0xffff0000, v15
	s_waitcnt vmcnt(3)
	v_mov_b32_e32 v2, v124
	v_mov_b32_e32 v3, v125
	v_mov_b32_e32 v4, v126
	v_mov_b32_e32 v5, v127
	v_lshlrev_b32_e32 v16, 16, v2
	v_and_b32_e32 v17, 0xffff0000, v2
	v_lshlrev_b32_e32 v2, 16, v3
	v_and_b32_e32 v3, 0xffff0000, v3
	v_lshlrev_b32_e32 v18, 16, v4
	v_and_b32_e32 v19, 0xffff0000, v4
	v_lshlrev_b32_e32 v4, 16, v5
	v_and_b32_e32 v5, 0xffff0000, v5
	v_mul_f32_e32 v0, 0xbfb8aa3b, v16
	v_mul_f32_e32 v20, 0xbfb8aa3b, v17
	v_mul_f32_e32 v21, 0xbfb8aa3b, v2
	v_mul_f32_e32 v22, 0xbfb8aa3b, v3
	v_mul_f32_e32 v23, 0xbfb8aa3b, v18
	v_mul_f32_e32 v24, 0xbfb8aa3b, v19
	v_mul_f32_e32 v25, 0xbfb8aa3b, v4
	v_mul_f32_e32 v26, 0xbfb8aa3b, v5
	v_exp_f32_e32 v0, v0
	v_exp_f32_e32 v20, v20
	v_exp_f32_e32 v21, v21
	v_exp_f32_e32 v22, v22
	v_exp_f32_e32 v23, v23
	v_exp_f32_e32 v24, v24
	v_exp_f32_e32 v25, v25
	v_exp_f32_e32 v26, v26
	v_add_f32_e32 v0, 1.0, v0
	v_add_f32_e32 v27, 1.0, v20
	v_add_f32_e32 v28, 1.0, v21
	v_add_f32_e32 v29, 1.0, v22
	v_add_f32_e32 v30, 1.0, v23
	v_add_f32_e32 v31, 1.0, v24
	v_add_f32_e32 v32, 1.0, v25
	v_add_f32_e32 v33, 1.0, v26
	v_rcp_f32_e32 v20, v0
	v_rcp_f32_e32 v21, v27
	v_rcp_f32_e32 v22, v28
	v_rcp_f32_e32 v23, v29
	v_rcp_f32_e32 v24, v30
	v_rcp_f32_e32 v25, v31
	v_rcp_f32_e32 v26, v32
	v_rcp_f32_e32 v27, v33
	v_pk_mul_f32 v[16:17], v[20:21], v[16:17]
	v_pk_mul_f32 v[2:3], v[22:23], v[2:3]
	v_pk_mul_f32 v[18:19], v[24:25], v[18:19]
	v_pk_mul_f32 v[4:5], v[26:27], v[4:5]
	v_pk_mul_f32 v[8:9], v[16:17], v[8:9]
	v_pk_mul_f32 v[10:11], v[2:3], v[10:11]
	v_pk_mul_f32 v[12:13], v[18:19], v[12:13]
	v_pk_mul_f32 v[14:15], v[4:5], v[14:15]
	v_cvt_pk_bf16_f32 v2, v8, v9
	v_cvt_pk_bf16_f32 v3, v10, v11
	v_cvt_pk_bf16_f32 v4, v12, v13
	v_cvt_pk_bf16_f32 v5, v14, v15
	global_store_dwordx4 v[6:7], v[2:5], off
	s_cbranch_scc1 .LBB0_793

; DI unsigned pack2(float a, float b) { f32x2_t v = {a, b}; bf16x2_t r = __builtin_convertvector(v, bf16x2_t); return __builtin_bit_cast(unsigned, r); }
; DI float bflo(unsigned u) { return __uint_as_float(u << 16); }
; DI float bfhi(unsigned u) { return __uint_as_float(u & 0xffff0000u); }
; DI float siluf_(float x) { return x * __builtin_amdgcn_rcpf(1.f + __expf(-x)); }
; DI void attn_write_staged(const f32x16& o0, const f32x16& o1, bf16_t* og, const bf16_t* z, size_t tok0, int head, int lane, bf16_t* wl) {
;   const int q = lane & 31, h = lane >> 5;
; #pragma unroll
;   for (int dt = 0; dt < 2; ++dt)
; #pragma unroll
;     for (int q4 = 0; q4 < 4; ++q4) {
;       const f32x16& o = dt ? o1 : o0;
;       *(uint2*)(wl + q * 72 + dt * 32 + 8 * q4 + 4 * h) = make_uint2(pack2(o[4 * q4], o[4 * q4 + 1]), pack2(o[4 * q4 + 2], o[4 * q4 + 3]));
;     }
; #pragma unroll
;   for (int k = 0; k < 4; ++k) {
;     const int ci = lane + 64 * k, row = ci >> 3, c8 = ci & 7;
;     const u32x4 ov = *(const u32x4*)(wl + row * 72 + c8 * 8);
;     const size_t off = (tok0 + row) * 1024 + head * 64 + c8 * 8;
;     const u32x4 zv = ldg16(z + off);
;     u32x4 r;
;     r.x = pack2(bflo(ov.x) * siluf_(bflo(zv.x)), bfhi(ov.x) * siluf_(bfhi(zv.x)));
;     r.y = pack2(bflo(ov.y) * siluf_(bflo(zv.y)), bfhi(ov.y) * siluf_(bfhi(zv.y)));
;     r.z = pack2(bflo(ov.z) * siluf_(bflo(zv.z)), bfhi(ov.z) * siluf_(bfhi(zv.z)));
;     r.w = pack2(bflo(ov.w) * siluf_(bflo(zv.w)), bfhi(ov.w) * siluf_(bfhi(zv.w)));
;     *(u32x4*)(og + off) = r;
;   }
; }
; DI void tot_addto(float* totL, int tid, f32x16& a, f32x16& b, float gi) {
; #pragma unroll
;   for (int k = 0; k < 4; ++k) {
;     const f32x4 v0 = *(const f32x4*)(totL + ((size_t)(k * 256 + tid)) * 4);
;     const f32x4 v1 = *(const f32x4*)(totL + ((size_t)((4 + k) * 256 + tid)) * 4);
;     a[4 * k] = v0.x + gi * a[4 * k]; a[4 * k + 1] = v0.y + gi * a[4 * k + 1]; a[4 * k + 2] = v0.z + gi * a[4 * k + 2]; a[4 * k + 3] = v0.w + gi * a[4 * k + 3];
;     b[4 * k] = v1.x + gi * b[4 * k]; b[4 * k + 1] = v1.y + gi * b[4 * k + 1]; b[4 * k + 2] = v1.z + gi * b[4 * k + 2]; b[4 * k + 3] = v1.w + gi * b[4 * k + 3];
;   }
; }
.LBB0_1273:
	s_mov_b32 s47, s45
	v_lshlrev_b32_e32 v41, 3, v137
	v_lshl_add_u64 v[34:35], v[134:135], 0, s[46:47]
	v_lshrrev_b32_e32 v0, 3, v137
	v_and_b32_e32 v41, 56, v41
	v_or_b32_e32 v70, v176, v41
	v_or_b32_e32 v34, v0, v34
	v_lshlrev_b64 v[74:75], 11, v[34:35]
	v_lshlrev_b32_e32 v76, 1, v70
	v_readlane_b32 s2, v246, 52
	v_or_b32_e32 v74, v74, v76
	v_readlane_b32 s3, v246, 53
	ds_read_b128 v[36:39], v180 offset:37376
	s_waitcnt vmcnt(3)
	ds_read_b128 v[42:45], v180 offset:41472
	s_waitcnt vmcnt(2)
	ds_read_b128 v[46:49], v180 offset:53760
	s_waitcnt vmcnt(1)
	ds_read_b128 v[50:53], v180 offset:57856
	s_waitcnt vmcnt(0)
	ds_read_b128 v[54:57], v180 offset:45568
	ds_read_b128 v[58:61], v180 offset:49664
	ds_read_b128 v[62:65], v180 offset:61952
	ds_read_b128 v[66:69], v181 offset:28672
	v_lshl_add_u64 v[70:71], s[2:3], 0, v[74:75]
	s_waitcnt lgkmcnt(0)
	s_barrier
	v_mov_b32_e32 v254, 0x4000
	v_mov_b32_e32 v255, 0
	v_lshl_add_u64 v[248:249], v[70:71], 0, v[254:255]
	v_lshl_add_u64 v[250:251], v[248:249], 0, v[254:255]
	v_lshl_add_u64 v[252:253], v[250:251], 0, v[254:255]
	global_load_dwordx4 v[70:73], v[70:71], off
	global_load_dwordx4 v[90:93], v[248:249], off
	global_load_dwordx4 v[94:97], v[250:251], off
	global_load_dwordx4 v[98:101], v[252:253], off
	v_div_scale_f32 v77, s[0:1], v40, v40, v179
	v_rcp_f32_e32 v81, v77
	s_movk_i32 s0, 0x1200
	v_mad_u32_u24 v80, v168, s0, v153
	v_mul_u32_u24_e32 v0, 0x90, v0
	v_lshlrev_b32_e32 v41, 1, v41
	v_add3_u32 v41, v80, v41, v0
	v_fma_f32 v0, -v77, v81, 1.0
	v_div_scale_f32 v78, vcc, v179, v40, v179
	v_lshrrev_b32_e32 v79, 2, v137
	v_fmac_f32_e32 v81, v0, v81
	v_and_b32_e32 v79, 8, v79
	v_mul_f32_e32 v0, v78, v81
	v_add3_u32 v79, v80, v175, v79
	v_fma_f32 v80, -v77, v0, v78
	v_fmac_f32_e32 v0, v80, v81
	v_fma_f32 v77, -v77, v0, v78
	v_div_fmas_f32 v0, v77, v81, v0
	v_div_fixup_f32 v0, v0, v40, v179
	v_pk_fma_f32 v[2:3], v[0:1], v[2:3], v[36:37] op_sel_hi:[0,1,1]
	v_pk_fma_f32 v[4:5], v[0:1], v[4:5], v[38:39] op_sel_hi:[0,1,1]
	v_pk_fma_f32 v[18:19], v[18:19], v[0:1], v[46:47] op_sel_hi:[1,0,1]
	v_pk_fma_f32 v[6:7], v[0:1], v[6:7], v[42:43] op_sel_hi:[0,1,1]
	v_pk_fma_f32 v[8:9], v[0:1], v[8:9], v[44:45] op_sel_hi:[0,1,1]
	v_pk_fma_f32 v[10:11], v[0:1], v[10:11], v[54:55] op_sel_hi:[0,1,1]
	v_pk_fma_f32 v[20:21], v[20:21], v[0:1], v[48:49] op_sel_hi:[1,0,1]
	v_pk_fma_f32 v[22:23], v[22:23], v[0:1], v[50:51] op_sel_hi:[1,0,1]
	v_pk_fma_f32 v[24:25], v[24:25], v[0:1], v[52:53] op_sel_hi:[1,0,1]
	v_pk_fma_f32 v[12:13], v[0:1], v[12:13], v[56:57] op_sel_hi:[0,1,1]
	v_pk_fma_f32 v[26:27], v[26:27], v[0:1], v[62:63] op_sel_hi:[1,0,1]
	v_pk_fma_f32 v[28:29], v[28:29], v[0:1], v[64:65] op_sel_hi:[1,0,1]
	v_pk_fma_f32 v[14:15], v[0:1], v[14:15], v[58:59] op_sel_hi:[0,1,1]
	v_pk_fma_f32 v[16:17], v[0:1], v[16:17], v[60:61] op_sel_hi:[0,1,1]
	v_pk_fma_f32 v[30:31], v[30:31], v[0:1], v[66:67] op_sel_hi:[1,0,1]
	v_pk_fma_f32 v[32:33], v[32:33], v[0:1], v[68:69] op_sel_hi:[1,0,1]
	v_cvt_pk_bf16_f32 v2, v2, v3
	v_cvt_pk_bf16_f32 v3, v4, v5
	v_cvt_pk_bf16_f32 v4, v6, v7
	v_cvt_pk_bf16_f32 v5, v8, v9
	v_cvt_pk_bf16_f32 v6, v10, v11
	v_cvt_pk_bf16_f32 v10, v18, v19
	v_cvt_pk_bf16_f32 v7, v12, v13
	v_cvt_pk_bf16_f32 v8, v14, v15
	v_cvt_pk_bf16_f32 v9, v16, v17
	v_cvt_pk_bf16_f32 v11, v20, v21
	v_cvt_pk_bf16_f32 v12, v22, v23
	v_cvt_pk_bf16_f32 v13, v24, v25
	v_cvt_pk_bf16_f32 v14, v26, v27
	v_cvt_pk_bf16_f32 v15, v28, v29
	v_cvt_pk_bf16_f32 v16, v30, v31
	v_cvt_pk_bf16_f32 v17, v32, v33
	ds_write2_b64 v79, v[2:3], v[4:5] offset1:2
	ds_write2_b64 v79, v[6:7], v[8:9] offset0:4 offset1:6
	ds_write2_b64 v79, v[10:11], v[12:13] offset0:8 offset1:10
	ds_write2_b64 v79, v[14:15], v[16:17] offset0:12 offset1:14
	ds_read_b128 v[2:5], v41
	ds_read_b128 v[6:9], v41 offset:1152
	s_waitcnt lgkmcnt(1)
	v_and_b32_e32 v13, 0xffff0000, v2
	s_waitcnt vmcnt(3)
	v_lshlrev_b32_e32 v10, 16, v70
	v_and_b32_e32 v11, 0xffff0000, v70
	v_mul_f32_e32 v0, 0xbfb8aa3b, v10
	v_mul_f32_e32 v12, 0xbfb8aa3b, v11
	v_exp_f32_e32 v0, v0
	v_exp_f32_e32 v14, v12
	v_lshlrev_b32_e32 v16, 16, v71
	v_lshlrev_b32_e32 v12, 16, v2
	v_add_f32_e32 v0, 1.0, v0
	v_add_f32_e32 v2, 1.0, v14
	v_rcp_f32_e32 v14, v0
	v_and_b32_e32 v17, 0xffff0000, v71
	v_mul_f32_e32 v0, 0xbfb8aa3b, v16
	v_rcp_f32_e32 v15, v2
	v_exp_f32_e32 v0, v0
	v_mul_f32_e32 v2, 0xbfb8aa3b, v17
	v_exp_f32_e32 v2, v2
	v_pk_mul_f32 v[10:11], v[14:15], v[10:11]
	v_add_f32_e32 v0, 1.0, v0
	v_pk_mul_f32 v[10:11], v[10:11], v[12:13]
	v_rcp_f32_e32 v12, v0
	v_add_f32_e32 v0, 1.0, v2
	v_lshlrev_b32_e32 v14, 16, v72
	v_rcp_f32_e32 v13, v0
	v_and_b32_e32 v15, 0xffff0000, v72
	v_mul_f32_e32 v0, 0xbfb8aa3b, v14
	v_cvt_pk_bf16_f32 v2, v10, v11
	v_lshlrev_b32_e32 v10, 16, v3
	v_and_b32_e32 v11, 0xffff0000, v3
	v_exp_f32_e32 v0, v0
	v_mul_f32_e32 v3, 0xbfb8aa3b, v15
	v_exp_f32_e32 v3, v3
	v_pk_mul_f32 v[12:13], v[12:13], v[16:17]
	v_add_f32_e32 v0, 1.0, v0
	v_pk_mul_f32 v[10:11], v[12:13], v[10:11]
	v_rcp_f32_e32 v12, v0
	v_add_f32_e32 v0, 1.0, v3
	v_rcp_f32_e32 v13, v0
	v_cvt_pk_bf16_f32 v3, v10, v11
	v_lshlrev_b32_e32 v10, 16, v4
	v_and_b32_e32 v11, 0xffff0000, v4
	v_pk_mul_f32 v[12:13], v[12:13], v[14:15]
	v_lshlrev_b32_e32 v14, 16, v73
	v_and_b32_e32 v15, 0xffff0000, v73
	v_mul_f32_e32 v0, 0xbfb8aa3b, v14
	v_exp_f32_e32 v0, v0
	v_mul_f32_e32 v4, 0xbfb8aa3b, v15
	v_exp_f32_e32 v4, v4
	v_pk_mul_f32 v[10:11], v[12:13], v[10:11]
	v_add_f32_e32 v0, 1.0, v0
	v_rcp_f32_e32 v12, v0
	v_add_f32_e32 v0, 1.0, v4
	v_rcp_f32_e32 v13, v0
	v_cvt_pk_bf16_f32 v4, v10, v11
	v_lshlrev_b32_e32 v10, 16, v5
	v_and_b32_e32 v11, 0xffff0000, v5
	v_pk_mul_f32 v[12:13], v[12:13], v[14:15]
	s_waitcnt lgkmcnt(0)
; DI unsigned pack2(float a, float b) { f32x2_t v = {a, b}; bf16x2_t r = __builtin_convertvector(v, bf16x2_t); return __builtin_bit_cast(unsigned, r); }
; DI float bflo(unsigned u) { return __uint_as_float(u << 16); }
; DI float bfhi(unsigned u) { return __uint_as_float(u & 0xffff0000u); }
; DI float siluf_(float x) { return x * __builtin_amdgcn_rcpf(1.f + __expf(-x)); }
; DI void attn_write_staged(const f32x16& o0, const f32x16& o1, bf16_t* og, const bf16_t* z, size_t tok0, int head, int lane, bf16_t* wl) {
;     ...
; #pragma unroll
;   for (int k = 0; k < 4; ++k) {
;     const int ci = lane + 64 * k, row = ci >> 3, c8 = ci & 7;
;     const u32x4 ov = *(const u32x4*)(wl + row * 72 + c8 * 8);
;     const size_t off = (tok0 + row) * 1024 + head * 64 + c8 * 8;
;     const u32x4 zv = ldg16(z + off);
;     u32x4 r;
;     r.x = pack2(bflo(ov.x) * siluf_(bflo(zv.x)), bfhi(ov.x) * siluf_(bfhi(zv.x)));
;     r.y = pack2(bflo(ov.y) * siluf_(bflo(zv.y)), bfhi(ov.y) * siluf_(bfhi(zv.y)));
;     r.z = pack2(bflo(ov.z) * siluf_(bflo(zv.z)), bfhi(ov.z) * siluf_(bfhi(zv.z)));
;     r.w = pack2(bflo(ov.w) * siluf_(bflo(zv.w)), bfhi(ov.w) * siluf_(bfhi(zv.w)));
;     *(u32x4*)(og + off) = r;
;   }
	v_lshlrev_b32_e32 v14, 16, v8
	v_pk_mul_f32 v[10:11], v[12:13], v[10:11]
	v_and_b32_e32 v15, 0xffff0000, v8
	v_cvt_pk_bf16_f32 v5, v10, v11
	v_lshl_add_u64 v[10:11], s[94:95], 0, v[74:75]
	global_store_dwordx4 v[10:11], v[2:5], off
	v_lshlrev_b32_e32 v12, 16, v6
	v_and_b32_e32 v13, 0xffff0000, v6
	v_or_b32_e32 v2, 8, v34
	v_mov_b32_e32 v3, v35
	v_lshlrev_b64 v[10:11], 11, v[2:3]
	v_or_b32_e32 v10, v10, v76
	v_lshl_add_u64 v[2:3], s[2:3], 0, v[10:11]
	v_lshlrev_b32_e32 v6, 16, v7
	v_and_b32_e32 v7, 0xffff0000, v7
	s_waitcnt vmcnt(3)
	v_mov_b32_e32 v2, v90
	v_mov_b32_e32 v3, v91
	v_mov_b32_e32 v4, v92
	v_mov_b32_e32 v5, v93
	v_lshlrev_b32_e32 v16, 16, v2
	v_and_b32_e32 v17, 0xffff0000, v2
	v_lshlrev_b32_e32 v2, 16, v3
	v_and_b32_e32 v3, 0xffff0000, v3
	v_lshlrev_b32_e32 v18, 16, v4
	v_and_b32_e32 v19, 0xffff0000, v4
	v_mul_f32_e32 v0, 0xbfb8aa3b, v16
	v_mul_f32_e32 v4, 0xbfb8aa3b, v17
	v_mul_f32_e32 v8, 0xbfb8aa3b, v2
	v_mul_f32_e32 v21, 0xbfb8aa3b, v3
	v_mul_f32_e32 v22, 0xbfb8aa3b, v18
	v_mul_f32_e32 v23, 0xbfb8aa3b, v19
	v_exp_f32_e32 v0, v0
	v_exp_f32_e32 v4, v4
	v_exp_f32_e32 v8, v8
	v_exp_f32_e32 v21, v21
	v_exp_f32_e32 v22, v22
	v_exp_f32_e32 v23, v23
	v_add_f32_e32 v0, 1.0, v0
	v_add_f32_e32 v4, 1.0, v4
	v_add_f32_e32 v8, 1.0, v8
	v_add_f32_e32 v21, 1.0, v21
	v_add_f32_e32 v26, 1.0, v22
	v_add_f32_e32 v27, 1.0, v23
	v_rcp_f32_e32 v22, v0
	v_rcp_f32_e32 v23, v4
	v_rcp_f32_e32 v24, v8
	v_rcp_f32_e32 v25, v21
	v_lshlrev_b32_e32 v20, 16, v5
	v_and_b32_e32 v21, 0xffff0000, v5
	v_pk_mul_f32 v[4:5], v[22:23], v[16:17]
	v_pk_mul_f32 v[2:3], v[24:25], v[2:3]
	v_pk_mul_f32 v[4:5], v[4:5], v[12:13]
	v_mul_f32_e32 v0, 0xbfb8aa3b, v20
	v_pk_mul_f32 v[6:7], v[2:3], v[6:7]
	v_cvt_pk_bf16_f32 v2, v4, v5
	v_exp_f32_e32 v0, v0
	v_mul_f32_e32 v4, 0xbfb8aa3b, v21
	v_cvt_pk_bf16_f32 v3, v6, v7
	v_exp_f32_e32 v7, v4
	v_add_f32_e32 v0, 1.0, v0
	v_rcp_f32_e32 v6, v0
	v_rcp_f32_e32 v26, v26
	v_add_f32_e32 v0, 1.0, v7
	v_rcp_f32_e32 v27, v27
	v_rcp_f32_e32 v7, v0
	v_lshlrev_b32_e32 v8, 16, v9
	v_and_b32_e32 v9, 0xffff0000, v9
	v_pk_mul_f32 v[16:17], v[26:27], v[18:19]
	v_pk_mul_f32 v[6:7], v[6:7], v[20:21]
	v_pk_mul_f32 v[4:5], v[16:17], v[14:15]
	v_pk_mul_f32 v[6:7], v[6:7], v[8:9]
	v_cvt_pk_bf16_f32 v4, v4, v5
	v_cvt_pk_bf16_f32 v5, v6, v7
	v_lshl_add_u64 v[6:7], s[94:95], 0, v[10:11]
	global_store_dwordx4 v[6:7], v[2:5], off
	ds_read_b128 v[6:9], v41 offset:2304
	s_nop 0
	v_or_b32_e32 v2, 16, v34
	v_mov_b32_e32 v3, v35
	v_lshlrev_b64 v[10:11], 11, v[2:3]
	v_or_b32_e32 v10, v10, v76
	v_lshl_add_u64 v[2:3], s[2:3], 0, v[10:11]
	v_or_b32_e32 v34, 24, v34
	v_lshlrev_b64 v[14:15], 11, v[34:35]
	v_lshl_add_u64 v[16:17], s[94:95], 0, v[10:11]
	ds_read_b128 v[10:13], v41 offset:3456
	s_waitcnt lgkmcnt(1)
	v_lshlrev_b32_e32 v20, 16, v6
	v_and_b32_e32 v21, 0xffff0000, v6
	v_lshlrev_b32_e32 v6, 16, v7
	v_and_b32_e32 v7, 0xffff0000, v7
	v_lshlrev_b32_e32 v22, 16, v8
	v_and_b32_e32 v23, 0xffff0000, v8
	v_lshlrev_b32_e32 v8, 16, v9
	v_and_b32_e32 v9, 0xffff0000, v9
	v_or_b32_e32 v14, v14, v76
	v_lshl_add_u64 v[18:19], s[2:3], 0, v[14:15]
	v_readlane_b32 s2, v245, 25
	s_add_i32 s2, s2, s74
	s_cmpk_gt_i32 s2, 0xfff
	s_waitcnt vmcnt(3)
	v_mov_b32_e32 v2, v94
	v_mov_b32_e32 v3, v95
	v_mov_b32_e32 v4, v96
	v_mov_b32_e32 v5, v97
	v_lshlrev_b32_e32 v24, 16, v2
	v_and_b32_e32 v25, 0xffff0000, v2
	v_lshlrev_b32_e32 v2, 16, v3
	v_and_b32_e32 v3, 0xffff0000, v3
	v_lshlrev_b32_e32 v26, 16, v4
	v_and_b32_e32 v27, 0xffff0000, v4
	v_lshlrev_b32_e32 v4, 16, v5
	v_and_b32_e32 v5, 0xffff0000, v5
	v_mul_f32_e32 v0, 0xbfb8aa3b, v24
	v_mul_f32_e32 v28, 0xbfb8aa3b, v25
	v_mul_f32_e32 v29, 0xbfb8aa3b, v2
	v_mul_f32_e32 v30, 0xbfb8aa3b, v3
	v_mul_f32_e32 v31, 0xbfb8aa3b, v26
	v_mul_f32_e32 v32, 0xbfb8aa3b, v27
	v_mul_f32_e32 v33, 0xbfb8aa3b, v4
	v_mul_f32_e32 v34, 0xbfb8aa3b, v5
	v_exp_f32_e32 v0, v0
	v_exp_f32_e32 v28, v28
	v_exp_f32_e32 v29, v29
	v_exp_f32_e32 v30, v30
	v_exp_f32_e32 v31, v31
	v_exp_f32_e32 v32, v32
	v_exp_f32_e32 v33, v33
	v_exp_f32_e32 v34, v34
	v_add_f32_e32 v0, 1.0, v0
	v_add_f32_e32 v35, 1.0, v28
	v_add_f32_e32 v36, 1.0, v29
	v_add_f32_e32 v37, 1.0, v30
	v_add_f32_e32 v38, 1.0, v31
	v_add_f32_e32 v39, 1.0, v32
	v_add_f32_e32 v40, 1.0, v33
	v_add_f32_e32 v41, 1.0, v34
	v_rcp_f32_e32 v28, v0
	v_rcp_f32_e32 v29, v35
	v_rcp_f32_e32 v30, v36
	v_rcp_f32_e32 v31, v37
	v_rcp_f32_e32 v32, v38
	v_rcp_f32_e32 v33, v39
	v_rcp_f32_e32 v34, v40
	v_rcp_f32_e32 v35, v41
	v_pk_mul_f32 v[24:25], v[28:29], v[24:25]
	v_pk_mul_f32 v[2:3], v[30:31], v[2:3]
	v_pk_mul_f32 v[26:27], v[32:33], v[26:27]
	v_pk_mul_f32 v[4:5], v[34:35], v[4:5]
	v_pk_mul_f32 v[20:21], v[24:25], v[20:21]
	v_pk_mul_f32 v[6:7], v[2:3], v[6:7]
	v_pk_mul_f32 v[22:23], v[26:27], v[22:23]
	v_pk_mul_f32 v[8:9], v[4:5], v[8:9]
	v_cvt_pk_bf16_f32 v2, v20, v21
	v_cvt_pk_bf16_f32 v3, v6, v7
	v_cvt_pk_bf16_f32 v4, v22, v23
	v_cvt_pk_bf16_f32 v5, v8, v9
	global_store_dwordx4 v[16:17], v[2:5], off
	v_lshl_add_u64 v[6:7], s[94:95], 0, v[14:15]
	s_waitcnt lgkmcnt(0)
	v_lshlrev_b32_e32 v8, 16, v10
	v_and_b32_e32 v9, 0xffff0000, v10
	v_lshlrev_b32_e32 v10, 16, v11
	v_and_b32_e32 v11, 0xffff0000, v11
	v_lshlrev_b32_e32 v14, 16, v12
	v_and_b32_e32 v15, 0xffff0000, v12
	v_lshlrev_b32_e32 v12, 16, v13
	v_and_b32_e32 v13, 0xffff0000, v13
	s_waitcnt vmcnt(3)
	v_mov_b32_e32 v2, v98
	v_mov_b32_e32 v3, v99
	v_mov_b32_e32 v4, v100
	v_mov_b32_e32 v5, v101
	v_lshlrev_b32_e32 v16, 16, v2
	v_and_b32_e32 v17, 0xffff0000, v2
	v_lshlrev_b32_e32 v2, 16, v3
	v_and_b32_e32 v3, 0xffff0000, v3
	v_lshlrev_b32_e32 v18, 16, v4
	v_and_b32_e32 v19, 0xffff0000, v4
	v_lshlrev_b32_e32 v4, 16, v5
	v_and_b32_e32 v5, 0xffff0000, v5
	v_mul_f32_e32 v0, 0xbfb8aa3b, v16
	v_mul_f32_e32 v20, 0xbfb8aa3b, v17
	v_mul_f32_e32 v21, 0xbfb8aa3b, v2
	v_mul_f32_e32 v22, 0xbfb8aa3b, v3
	v_mul_f32_e32 v23, 0xbfb8aa3b, v18
	v_mul_f32_e32 v24, 0xbfb8aa3b, v19
	v_mul_f32_e32 v25, 0xbfb8aa3b, v4
	v_mul_f32_e32 v26, 0xbfb8aa3b, v5
	v_exp_f32_e32 v0, v0
	v_exp_f32_e32 v20, v20
	v_exp_f32_e32 v21, v21
	v_exp_f32_e32 v22, v22
	v_exp_f32_e32 v23, v23
	v_exp_f32_e32 v24, v24
	v_exp_f32_e32 v25, v25
	v_exp_f32_e32 v26, v26
	v_add_f32_e32 v0, 1.0, v0
	v_add_f32_e32 v27, 1.0, v20
	v_add_f32_e32 v28, 1.0, v21
	v_add_f32_e32 v29, 1.0, v22
	v_add_f32_e32 v30, 1.0, v23
	v_add_f32_e32 v31, 1.0, v24
	v_add_f32_e32 v32, 1.0, v25
	v_add_f32_e32 v33, 1.0, v26
	v_rcp_f32_e32 v20, v0
	v_rcp_f32_e32 v21, v27
	v_rcp_f32_e32 v22, v28
	v_rcp_f32_e32 v23, v29
	v_rcp_f32_e32 v24, v30
	v_rcp_f32_e32 v25, v31
	v_rcp_f32_e32 v26, v32
	v_rcp_f32_e32 v27, v33
	v_pk_mul_f32 v[16:17], v[20:21], v[16:17]
	v_pk_mul_f32 v[2:3], v[22:23], v[2:3]
	v_pk_mul_f32 v[18:19], v[24:25], v[18:19]
	v_pk_mul_f32 v[4:5], v[26:27], v[4:5]
	v_pk_mul_f32 v[8:9], v[16:17], v[8:9]
	v_pk_mul_f32 v[10:11], v[2:3], v[10:11]
	v_pk_mul_f32 v[14:15], v[18:19], v[14:15]
	v_pk_mul_f32 v[12:13], v[4:5], v[12:13]
	v_cvt_pk_bf16_f32 v2, v8, v9
	v_cvt_pk_bf16_f32 v3, v10, v11
	v_cvt_pk_bf16_f32 v4, v14, v15
	v_cvt_pk_bf16_f32 v5, v12, v13
	global_store_dwordx4 v[6:7], v[2:5], off
	s_barrier
	s_cbranch_scc1 .LBB0_1371

; DI unsigned pack2(float a, float b) { f32x2_t v = {a, b}; bf16x2_t r = __builtin_convertvector(v, bf16x2_t); return __builtin_bit_cast(unsigned, r); }
; DI float bflo(unsigned u) { return __uint_as_float(u << 16); }
; DI float bfhi(unsigned u) { return __uint_as_float(u & 0xffff0000u); }
; DI float siluf_(float x) { return x * __builtin_amdgcn_rcpf(1.f + __expf(-x)); }
; DI void attn_write_staged(const f32x16& o0, const f32x16& o1, bf16_t* og, const bf16_t* z, size_t tok0, int head, int lane, bf16_t* wl) {
;   const int q = lane & 31, h = lane >> 5;
; #pragma unroll
;   for (int dt = 0; dt < 2; ++dt)
; #pragma unroll
;     for (int q4 = 0; q4 < 4; ++q4) {
;       const f32x16& o = dt ? o1 : o0;
;       *(uint2*)(wl + q * 72 + dt * 32 + 8 * q4 + 4 * h) = make_uint2(pack2(o[4 * q4], o[4 * q4 + 1]), pack2(o[4 * q4 + 2], o[4 * q4 + 3]));
;     }
; #pragma unroll
;   for (int k = 0; k < 4; ++k) {
;     const int ci = lane + 64 * k, row = ci >> 3, c8 = ci & 7;
;     const u32x4 ov = *(const u32x4*)(wl + row * 72 + c8 * 8);
;     const size_t off = (tok0 + row) * 1024 + head * 64 + c8 * 8;
;     const u32x4 zv = ldg16(z + off);
;     u32x4 r;
;     r.x = pack2(bflo(ov.x) * siluf_(bflo(zv.x)), bfhi(ov.x) * siluf_(bfhi(zv.x)));
;     r.y = pack2(bflo(ov.y) * siluf_(bflo(zv.y)), bfhi(ov.y) * siluf_(bfhi(zv.y)));
;     r.z = pack2(bflo(ov.z) * siluf_(bflo(zv.z)), bfhi(ov.z) * siluf_(bfhi(zv.z)));
;     r.w = pack2(bflo(ov.w) * siluf_(bflo(zv.w)), bfhi(ov.w) * siluf_(bfhi(zv.w)));
;     *(u32x4*)(og + off) = r;
;   }
; }
; DI void phase_attn_swa(const Params& P, const float* sinks, bf16_t* og, unsigned char* smem, int L, int G) {
;     ...
;     const float il = 1.f / l;
; #pragma unroll
;     for (int q = 0; q < 16; ++q) { o0[q] *= il; o1[q] *= il; }
;     attn_write_staged(o0, o1, og, big + SW_Z, (size_t)b * SEQ + t0, head, lane, (bf16_t*)(smem + 40960) + w * (32 * 72));
.LBB0_1659:
	s_mov_b32 s11, s9
	v_lshlrev_b32_e32 v35, 6, v173
	v_lshl_add_u64 v[32:33], v[148:149], 0, s[10:11]
	v_or_b32_e32 v35, v35, v130
	v_or_b32_e32 v36, v32, v132
	v_mov_b32_e32 v37, v33
	v_lshlrev_b64 v[40:41], 11, v[36:37]
	v_lshlrev_b32_e32 v35, 1, v35
	v_or_b32_e32 v40, v40, v35
	v_lshl_add_u64 v[36:37], s[6:7], 0, v[40:41]
	v_mov_b32_e32 v254, 0x4000
	v_mov_b32_e32 v255, 0
	v_lshl_add_u64 v[248:249], v[36:37], 0, v[254:255]
	v_lshl_add_u64 v[250:251], v[248:249], 0, v[254:255]
	v_lshl_add_u64 v[252:253], v[250:251], 0, v[254:255]
	global_load_dwordx4 v[36:39], v[36:37], off
	global_load_dwordx4 v[96:99], v[248:249], off
	global_load_dwordx4 v[100:103], v[250:251], off
	global_load_dwordx4 v[104:107], v[252:253], off
	v_div_scale_f32 v42, s[0:1], v34, v34, 1.0
	v_rcp_f32_e32 v43, v42
	v_div_scale_f32 v44, vcc, 1.0, v34, 1.0
	v_add_u32_e32 v45, 0xa000, v166
	v_fma_f32 v46, -v42, v43, 1.0
	v_fmac_f32_e32 v43, v46, v43
	v_mul_f32_e32 v46, v44, v43
	v_fma_f32 v47, -v42, v46, v44
	v_fmac_f32_e32 v46, v47, v43
	v_fma_f32 v42, -v42, v46, v44
	v_div_fmas_f32 v42, v42, v43, v46
	v_div_fixup_f32 v34, v42, v34, 1.0
	v_pk_mul_f32 v[0:1], v[34:35], v[0:1] op_sel_hi:[0,1]
	v_pk_mul_f32 v[2:3], v[34:35], v[2:3] op_sel_hi:[0,1]
	v_pk_mul_f32 v[4:5], v[34:35], v[4:5] op_sel_hi:[0,1]
	v_pk_mul_f32 v[20:21], v[20:21], v[34:35] op_sel_hi:[1,0]
	v_pk_mul_f32 v[6:7], v[34:35], v[6:7] op_sel_hi:[0,1]
	v_pk_mul_f32 v[22:23], v[22:23], v[34:35] op_sel_hi:[1,0]
	v_pk_mul_f32 v[24:25], v[24:25], v[34:35] op_sel_hi:[1,0]
	v_pk_mul_f32 v[10:11], v[34:35], v[10:11] op_sel_hi:[0,1]
	v_pk_mul_f32 v[26:27], v[26:27], v[34:35] op_sel_hi:[1,0]
	v_pk_mul_f32 v[12:13], v[34:35], v[12:13] op_sel_hi:[0,1]
	v_pk_mul_f32 v[16:17], v[16:17], v[34:35] op_sel_hi:[1,0]
	v_pk_mul_f32 v[18:19], v[18:19], v[34:35] op_sel_hi:[1,0]
	v_pk_mul_f32 v[8:9], v[34:35], v[8:9] op_sel_hi:[0,1]
	v_pk_mul_f32 v[28:29], v[28:29], v[34:35] op_sel_hi:[1,0]
	v_pk_mul_f32 v[14:15], v[34:35], v[14:15] op_sel_hi:[0,1]
	v_pk_mul_f32 v[30:31], v[30:31], v[34:35] op_sel_hi:[1,0]
	v_cvt_pk_bf16_f32 v0, v0, v1
	v_cvt_pk_bf16_f32 v1, v2, v3
	v_cvt_pk_bf16_f32 v2, v4, v5
	v_cvt_pk_bf16_f32 v3, v6, v7
	v_cvt_pk_bf16_f32 v5, v10, v11
	v_cvt_pk_bf16_f32 v6, v12, v13
	v_cvt_pk_bf16_f32 v10, v20, v21
	v_cvt_pk_bf16_f32 v11, v22, v23
	v_cvt_pk_bf16_f32 v12, v24, v25
	v_cvt_pk_bf16_f32 v13, v26, v27
	v_cvt_pk_bf16_f32 v4, v8, v9
	v_cvt_pk_bf16_f32 v7, v14, v15
	v_cvt_pk_bf16_f32 v8, v16, v17
	v_cvt_pk_bf16_f32 v9, v18, v19
	v_cvt_pk_bf16_f32 v14, v28, v29
	v_cvt_pk_bf16_f32 v15, v30, v31
	ds_write2_b64 v45, v[0:1], v[2:3] offset1:2
	ds_write2_b64 v45, v[4:5], v[6:7] offset0:4 offset1:6
	ds_write2_b64 v45, v[8:9], v[10:11] offset0:8 offset1:10
	ds_write2_b64 v45, v[12:13], v[14:15] offset0:12 offset1:14
	ds_read_b128 v[0:3], v167 offset:40960
	ds_read_b128 v[4:7], v167 offset:42112
	s_add_i32 s16, s16, s74
	s_cmpk_gt_i32 s16, 0xfff
	s_waitcnt lgkmcnt(1)
	v_lshlrev_b32_e32 v8, 16, v0
	v_and_b32_e32 v9, 0xffff0000, v0
	v_lshlrev_b32_e32 v0, 16, v1
	v_and_b32_e32 v1, 0xffff0000, v1
	s_waitcnt vmcnt(3)
	v_lshlrev_b32_e32 v10, 16, v36
	v_and_b32_e32 v11, 0xffff0000, v36
	v_lshlrev_b32_e32 v12, 16, v37
	v_and_b32_e32 v13, 0xffff0000, v37
	v_mul_f32_e32 v16, 0xbfb8aa3b, v10
	v_mul_f32_e32 v17, 0xbfb8aa3b, v11
	v_mul_f32_e32 v18, 0xbfb8aa3b, v12
	v_mul_f32_e32 v19, 0xbfb8aa3b, v13
	v_exp_f32_e32 v16, v16
	v_exp_f32_e32 v17, v17
	v_exp_f32_e32 v18, v18
	v_exp_f32_e32 v19, v19
	v_lshlrev_b32_e32 v14, 16, v38
	v_and_b32_e32 v15, 0xffff0000, v38
	v_add_f32_e32 v16, 1.0, v16
	v_add_f32_e32 v17, 1.0, v17
	v_add_f32_e32 v18, 1.0, v18
	v_add_f32_e32 v19, 1.0, v19
	v_mul_f32_e32 v20, 0xbfb8aa3b, v14
	v_mul_f32_e32 v21, 0xbfb8aa3b, v15
	v_rcp_f32_e32 v16, v16
	v_rcp_f32_e32 v17, v17
	v_rcp_f32_e32 v18, v18
	v_rcp_f32_e32 v19, v19
	v_exp_f32_e32 v20, v20
	v_exp_f32_e32 v21, v21
	v_pk_mul_f32 v[10:11], v[16:17], v[10:11]
	v_pk_mul_f32 v[12:13], v[18:19], v[12:13]
	v_add_f32_e32 v20, 1.0, v20
	v_pk_mul_f32 v[8:9], v[10:11], v[8:9]
	v_pk_mul_f32 v[10:11], v[12:13], v[0:1]
	v_add_f32_e32 v1, 1.0, v21
	v_rcp_f32_e32 v20, v20
	v_rcp_f32_e32 v21, v1
	v_lshlrev_b32_e32 v12, 16, v39
	v_cvt_pk_bf16_f32 v0, v8, v9
	v_lshlrev_b32_e32 v8, 16, v2
	v_and_b32_e32 v9, 0xffff0000, v2
	v_and_b32_e32 v13, 0xffff0000, v39
	v_mul_f32_e32 v2, 0xbfb8aa3b, v12
	v_cvt_pk_bf16_f32 v1, v10, v11
	v_pk_mul_f32 v[10:11], v[20:21], v[14:15]
	v_exp_f32_e32 v2, v2
	v_mul_f32_e32 v14, 0xbfb8aa3b, v13
	v_exp_f32_e32 v14, v14
	v_pk_mul_f32 v[8:9], v[10:11], v[8:9]
	v_add_f32_e32 v2, 1.0, v2
	v_rcp_f32_e32 v10, v2
	v_add_f32_e32 v2, 1.0, v14
	v_rcp_f32_e32 v11, v2
	v_cvt_pk_bf16_f32 v2, v8, v9
	v_lshlrev_b32_e32 v8, 16, v3
	v_and_b32_e32 v9, 0xffff0000, v3
	v_pk_mul_f32 v[10:11], v[10:11], v[12:13]
	s_waitcnt lgkmcnt(0)
	v_lshlrev_b32_e32 v12, 16, v4
	v_pk_mul_f32 v[8:9], v[10:11], v[8:9]
	v_or_b32_e32 v10, v32, v136
	v_cvt_pk_bf16_f32 v3, v8, v9
	v_lshl_add_u64 v[8:9], s[94:95], 0, v[40:41]
	global_store_dwordx4 v[8:9], v[0:3], off
	v_mov_b32_e32 v11, v33
	v_and_b32_e32 v13, 0xffff0000, v4
	v_or_b32_e32 v0, v32, v134
	v_mov_b32_e32 v1, v33
	v_lshlrev_b64 v[8:9], 11, v[0:1]
	v_or_b32_e32 v8, v8, v35
	v_lshl_add_u64 v[0:1], s[6:7], 0, v[8:9]
	v_lshlrev_b32_e32 v4, 16, v5
	v_and_b32_e32 v5, 0xffff0000, v5
	v_lshlrev_b32_e32 v14, 16, v6
	v_and_b32_e32 v15, 0xffff0000, v6
	v_lshlrev_b32_e32 v6, 16, v7
	v_and_b32_e32 v7, 0xffff0000, v7
	v_lshlrev_b64 v[10:11], 11, v[10:11]
	v_lshl_add_u64 v[8:9], s[94:95], 0, v[8:9]
	v_or_b32_e32 v10, v10, v35
	v_or_b32_e32 v32, v32, v138
	s_waitcnt vmcnt(3)
; DI unsigned pack2(float a, float b) { f32x2_t v = {a, b}; bf16x2_t r = __builtin_convertvector(v, bf16x2_t); return __builtin_bit_cast(unsigned, r); }
; DI float bflo(unsigned u) { return __uint_as_float(u << 16); }
; DI float bfhi(unsigned u) { return __uint_as_float(u & 0xffff0000u); }
; DI float siluf_(float x) { return x * __builtin_amdgcn_rcpf(1.f + __expf(-x)); }
; DI void attn_write_staged(const f32x16& o0, const f32x16& o1, bf16_t* og, const bf16_t* z, size_t tok0, int head, int lane, bf16_t* wl) {
;     ...
; #pragma unroll
;   for (int k = 0; k < 4; ++k) {
;     const int ci = lane + 64 * k, row = ci >> 3, c8 = ci & 7;
;     const u32x4 ov = *(const u32x4*)(wl + row * 72 + c8 * 8);
;     const size_t off = (tok0 + row) * 1024 + head * 64 + c8 * 8;
;     const u32x4 zv = ldg16(z + off);
;     u32x4 r;
;     r.x = pack2(bflo(ov.x) * siluf_(bflo(zv.x)), bfhi(ov.x) * siluf_(bfhi(zv.x)));
;     r.y = pack2(bflo(ov.y) * siluf_(bflo(zv.y)), bfhi(ov.y) * siluf_(bfhi(zv.y)));
;     r.z = pack2(bflo(ov.z) * siluf_(bflo(zv.z)), bfhi(ov.z) * siluf_(bfhi(zv.z)));
;     r.w = pack2(bflo(ov.w) * siluf_(bflo(zv.w)), bfhi(ov.w) * siluf_(bfhi(zv.w)));
;     *(u32x4*)(og + off) = r;
;   }
	v_mov_b32_e32 v0, v96
	v_mov_b32_e32 v1, v97
	v_mov_b32_e32 v2, v98
	v_mov_b32_e32 v3, v99
	v_lshlrev_b32_e32 v16, 16, v0
	v_and_b32_e32 v17, 0xffff0000, v0
	v_lshlrev_b32_e32 v0, 16, v1
	v_and_b32_e32 v1, 0xffff0000, v1
	v_lshlrev_b32_e32 v18, 16, v2
	v_and_b32_e32 v19, 0xffff0000, v2
	v_lshlrev_b32_e32 v2, 16, v3
	v_and_b32_e32 v3, 0xffff0000, v3
	v_mul_f32_e32 v20, 0xbfb8aa3b, v16
	v_mul_f32_e32 v21, 0xbfb8aa3b, v17
	v_mul_f32_e32 v22, 0xbfb8aa3b, v0
	v_mul_f32_e32 v23, 0xbfb8aa3b, v1
	v_mul_f32_e32 v24, 0xbfb8aa3b, v18
	v_mul_f32_e32 v25, 0xbfb8aa3b, v19
	v_mul_f32_e32 v26, 0xbfb8aa3b, v2
	v_mul_f32_e32 v27, 0xbfb8aa3b, v3
	v_exp_f32_e32 v20, v20
	v_exp_f32_e32 v21, v21
	v_exp_f32_e32 v22, v22
	v_exp_f32_e32 v23, v23
	v_exp_f32_e32 v24, v24
	v_exp_f32_e32 v25, v25
	v_exp_f32_e32 v26, v26
	v_exp_f32_e32 v27, v27
	v_add_f32_e32 v20, 1.0, v20
	v_add_f32_e32 v21, 1.0, v21
	v_add_f32_e32 v22, 1.0, v22
	v_add_f32_e32 v23, 1.0, v23
	v_add_f32_e32 v24, 1.0, v24
	v_add_f32_e32 v25, 1.0, v25
	v_add_f32_e32 v26, 1.0, v26
	v_add_f32_e32 v27, 1.0, v27
	v_rcp_f32_e32 v20, v20
	v_rcp_f32_e32 v21, v21
	v_rcp_f32_e32 v22, v22
	v_rcp_f32_e32 v23, v23
	v_rcp_f32_e32 v24, v24
	v_rcp_f32_e32 v25, v25
	v_rcp_f32_e32 v26, v26
	v_rcp_f32_e32 v27, v27
	v_pk_mul_f32 v[16:17], v[20:21], v[16:17]
	v_pk_mul_f32 v[0:1], v[22:23], v[0:1]
	v_pk_mul_f32 v[18:19], v[24:25], v[18:19]
	v_pk_mul_f32 v[2:3], v[26:27], v[2:3]
	v_pk_mul_f32 v[12:13], v[16:17], v[12:13]
	v_pk_mul_f32 v[4:5], v[0:1], v[4:5]
	v_pk_mul_f32 v[14:15], v[18:19], v[14:15]
	v_pk_mul_f32 v[6:7], v[2:3], v[6:7]
	v_cvt_pk_bf16_f32 v0, v12, v13
	v_cvt_pk_bf16_f32 v1, v4, v5
	v_cvt_pk_bf16_f32 v2, v14, v15
	v_cvt_pk_bf16_f32 v3, v6, v7
	global_store_dwordx4 v[8:9], v[0:3], off
	v_lshlrev_b64 v[12:13], 11, v[32:33]
	ds_read_b128 v[4:7], v167 offset:43264
	v_lshl_add_u64 v[0:1], s[6:7], 0, v[10:11]
	v_lshl_add_u64 v[14:15], s[94:95], 0, v[10:11]
	ds_read_b128 v[8:11], v167 offset:44416
	s_waitcnt lgkmcnt(1)
	v_lshlrev_b32_e32 v18, 16, v4
	v_and_b32_e32 v19, 0xffff0000, v4
	v_lshlrev_b32_e32 v4, 16, v5
	v_and_b32_e32 v5, 0xffff0000, v5
	v_lshlrev_b32_e32 v20, 16, v6
	v_and_b32_e32 v21, 0xffff0000, v6
	v_lshlrev_b32_e32 v6, 16, v7
	v_and_b32_e32 v7, 0xffff0000, v7
	v_or_b32_e32 v12, v12, v35
	v_lshl_add_u64 v[16:17], s[6:7], 0, v[12:13]
	s_waitcnt vmcnt(3)
	v_mov_b32_e32 v0, v100
	v_mov_b32_e32 v1, v101
	v_mov_b32_e32 v2, v102
	v_mov_b32_e32 v3, v103
	v_lshlrev_b32_e32 v22, 16, v0
	v_and_b32_e32 v23, 0xffff0000, v0
	v_lshlrev_b32_e32 v0, 16, v1
	v_and_b32_e32 v1, 0xffff0000, v1
	v_lshlrev_b32_e32 v24, 16, v2
	v_and_b32_e32 v25, 0xffff0000, v2
	v_lshlrev_b32_e32 v2, 16, v3
	v_and_b32_e32 v3, 0xffff0000, v3
	v_mul_f32_e32 v26, 0xbfb8aa3b, v22
	v_mul_f32_e32 v27, 0xbfb8aa3b, v23
	v_mul_f32_e32 v28, 0xbfb8aa3b, v0
	v_mul_f32_e32 v29, 0xbfb8aa3b, v1
	v_mul_f32_e32 v30, 0xbfb8aa3b, v24
	v_mul_f32_e32 v31, 0xbfb8aa3b, v25
	v_mul_f32_e32 v32, 0xbfb8aa3b, v2
	v_mul_f32_e32 v33, 0xbfb8aa3b, v3
	v_exp_f32_e32 v26, v26
	v_exp_f32_e32 v27, v27
	v_exp_f32_e32 v28, v28
	v_exp_f32_e32 v29, v29
	v_exp_f32_e32 v30, v30
	v_exp_f32_e32 v31, v31
	v_exp_f32_e32 v32, v32
	v_exp_f32_e32 v33, v33
	v_add_f32_e32 v26, 1.0, v26
	v_add_f32_e32 v27, 1.0, v27
	v_add_f32_e32 v28, 1.0, v28
	v_add_f32_e32 v29, 1.0, v29
	v_add_f32_e32 v30, 1.0, v30
	v_add_f32_e32 v31, 1.0, v31
	v_add_f32_e32 v32, 1.0, v32
	v_add_f32_e32 v33, 1.0, v33
	v_rcp_f32_e32 v26, v26
	v_rcp_f32_e32 v27, v27
	v_rcp_f32_e32 v28, v28
	v_rcp_f32_e32 v29, v29
	v_rcp_f32_e32 v30, v30
	v_rcp_f32_e32 v31, v31
	v_rcp_f32_e32 v32, v32
	v_rcp_f32_e32 v33, v33
	v_pk_mul_f32 v[22:23], v[26:27], v[22:23]
	v_pk_mul_f32 v[0:1], v[28:29], v[0:1]
	v_pk_mul_f32 v[24:25], v[30:31], v[24:25]
	v_pk_mul_f32 v[2:3], v[32:33], v[2:3]
	v_pk_mul_f32 v[18:19], v[22:23], v[18:19]
	v_pk_mul_f32 v[4:5], v[0:1], v[4:5]
	v_pk_mul_f32 v[20:21], v[24:25], v[20:21]
	v_pk_mul_f32 v[6:7], v[2:3], v[6:7]
	v_cvt_pk_bf16_f32 v0, v18, v19
	v_cvt_pk_bf16_f32 v1, v4, v5
	v_cvt_pk_bf16_f32 v2, v20, v21
	v_cvt_pk_bf16_f32 v3, v6, v7
	global_store_dwordx4 v[14:15], v[0:3], off
	v_lshl_add_u64 v[4:5], s[94:95], 0, v[12:13]
	s_waitcnt lgkmcnt(0)
	v_lshlrev_b32_e32 v6, 16, v8
	v_and_b32_e32 v7, 0xffff0000, v8
	v_lshlrev_b32_e32 v8, 16, v9
	v_and_b32_e32 v9, 0xffff0000, v9
	v_lshlrev_b32_e32 v12, 16, v10
	v_and_b32_e32 v13, 0xffff0000, v10
	v_lshlrev_b32_e32 v10, 16, v11
	v_and_b32_e32 v11, 0xffff0000, v11
	s_waitcnt vmcnt(3)
	v_mov_b32_e32 v0, v104
	v_mov_b32_e32 v1, v105
	v_mov_b32_e32 v2, v106
	v_mov_b32_e32 v3, v107
	v_lshlrev_b32_e32 v14, 16, v0
	v_and_b32_e32 v15, 0xffff0000, v0
	v_lshlrev_b32_e32 v0, 16, v1
	v_and_b32_e32 v1, 0xffff0000, v1
	v_lshlrev_b32_e32 v16, 16, v2
	v_and_b32_e32 v17, 0xffff0000, v2
	v_lshlrev_b32_e32 v2, 16, v3
	v_and_b32_e32 v3, 0xffff0000, v3
	v_mul_f32_e32 v18, 0xbfb8aa3b, v14
	v_mul_f32_e32 v19, 0xbfb8aa3b, v15
	v_mul_f32_e32 v20, 0xbfb8aa3b, v0
	v_mul_f32_e32 v21, 0xbfb8aa3b, v1
	v_mul_f32_e32 v22, 0xbfb8aa3b, v16
	v_mul_f32_e32 v23, 0xbfb8aa3b, v17
	v_mul_f32_e32 v24, 0xbfb8aa3b, v2
	v_mul_f32_e32 v25, 0xbfb8aa3b, v3
	v_exp_f32_e32 v18, v18
	v_exp_f32_e32 v19, v19
	v_exp_f32_e32 v20, v20
	v_exp_f32_e32 v21, v21
	v_exp_f32_e32 v22, v22
	v_exp_f32_e32 v23, v23
	v_exp_f32_e32 v24, v24
	v_exp_f32_e32 v25, v25
	v_add_f32_e32 v18, 1.0, v18
	v_add_f32_e32 v19, 1.0, v19
	v_add_f32_e32 v20, 1.0, v20
	v_add_f32_e32 v21, 1.0, v21
	v_add_f32_e32 v22, 1.0, v22
	v_add_f32_e32 v23, 1.0, v23
	v_add_f32_e32 v24, 1.0, v24
	v_add_f32_e32 v25, 1.0, v25
	v_rcp_f32_e32 v18, v18
	v_rcp_f32_e32 v19, v19
	v_rcp_f32_e32 v20, v20
	v_rcp_f32_e32 v21, v21
	v_rcp_f32_e32 v22, v22
	v_rcp_f32_e32 v23, v23
	v_rcp_f32_e32 v24, v24
	v_rcp_f32_e32 v25, v25
	v_pk_mul_f32 v[14:15], v[18:19], v[14:15]
	v_pk_mul_f32 v[0:1], v[20:21], v[0:1]
	v_pk_mul_f32 v[16:17], v[22:23], v[16:17]
	v_pk_mul_f32 v[2:3], v[24:25], v[2:3]
	v_pk_mul_f32 v[6:7], v[14:15], v[6:7]
	v_pk_mul_f32 v[8:9], v[0:1], v[8:9]
	v_pk_mul_f32 v[12:13], v[16:17], v[12:13]
	v_pk_mul_f32 v[10:11], v[2:3], v[10:11]
	v_cvt_pk_bf16_f32 v0, v6, v7
	v_cvt_pk_bf16_f32 v1, v8, v9
	v_cvt_pk_bf16_f32 v2, v12, v13
	v_cvt_pk_bf16_f32 v3, v10, v11
	global_store_dwordx4 v[4:5], v[0:3], off
	s_cbranch_scc1 .LBB0_1674

; __global__ void __launch_bounds__(512, 2) mega_fwd(Params P) {
;   __shared__ __attribute__((aligned(16))) unsigned char smem[LDS_BYTES];
	.amdhsa_kernel _Z8mega_fwd6Params
		.amdhsa_group_segment_fixed_size 153616
		.amdhsa_private_segment_fixed_size 0
		.amdhsa_kernarg_size 456
		.amdhsa_user_sgpr_count 2
		.amdhsa_user_sgpr_dispatch_ptr 0
		.amdhsa_user_sgpr_queue_ptr 0
		.amdhsa_user_sgpr_kernarg_segment_ptr 1
		.amdhsa_user_sgpr_dispatch_id 0
		.amdhsa_user_sgpr_kernarg_preload_length 0
		.amdhsa_user_sgpr_kernarg_preload_offset 0
		.amdhsa_user_sgpr_private_segment_size 0
		.amdhsa_uses_dynamic_stack 0
		.amdhsa_enable_private_segment 0
		.amdhsa_system_sgpr_workgroup_id_x 1
		.amdhsa_system_sgpr_workgroup_id_y 0
		.amdhsa_system_sgpr_workgroup_id_z 0
		.amdhsa_system_sgpr_workgroup_info 0
		.amdhsa_system_vgpr_workitem_id 2
		.amdhsa_next_free_vgpr 256
		.amdhsa_next_free_sgpr 100
		.amdhsa_accum_offset 256
		.amdhsa_reserve_vcc 1
		.amdhsa_float_round_mode_32 0
		.amdhsa_float_round_mode_16_64 0
		.amdhsa_float_denorm_mode_32 3
		.amdhsa_float_denorm_mode_16_64 3
		.amdhsa_dx10_clamp 1
		.amdhsa_ieee_mode 1
		.amdhsa_fp16_overflow 0
		.amdhsa_tg_split 0
		.amdhsa_exception_fp_ieee_invalid_op 0
		.amdhsa_exception_fp_denorm_src 0
		.amdhsa_exception_fp_ieee_div_zero 0
		.amdhsa_exception_fp_ieee_overflow 0
		.amdhsa_exception_fp_ieee_underflow 0
		.amdhsa_exception_fp_ieee_inexact 0
		.amdhsa_exception_int_div_zero 0
	.end_amdhsa_kernel

; __global__ void __launch_bounds__(512, 2) mega_fwd(Params P) {
;   __shared__ __attribute__((aligned(16))) unsigned char smem[LDS_BYTES];
amdhsa.kernels:
  - .agpr_count:     0
    .args:
      - .offset:         0
        .size:           200
        .value_kind:     by_value
      - .offset:         200
        .size:           4
        .value_kind:     hidden_block_count_x
      - .offset:         204
        .size:           4
        .value_kind:     hidden_block_count_y
      - .offset:         208
        .size:           4
        .value_kind:     hidden_block_count_z
      - .offset:         212
        .size:           2
        .value_kind:     hidden_group_size_x
      - .offset:         214
        .size:           2
        .value_kind:     hidden_group_size_y
      - .offset:         216
        .size:           2
        .value_kind:     hidden_group_size_z
      - .offset:         218
        .size:           2
        .value_kind:     hidden_remainder_x
      - .offset:         220
        .size:           2
        .value_kind:     hidden_remainder_y
      - .offset:         222
        .size:           2
        .value_kind:     hidden_remainder_z
      - .offset:         240
        .size:           8
        .value_kind:     hidden_global_offset_x
      - .offset:         248
        .size:           8
        .value_kind:     hidden_global_offset_y
      - .offset:         256
        .size:           8
        .value_kind:     hidden_global_offset_z
      - .offset:         264
        .size:           2
        .value_kind:     hidden_grid_dims
      - .offset:         288
        .size:           8
        .value_kind:     hidden_multigrid_sync_arg
    .group_segment_fixed_size: 153616
    .kernarg_segment_align: 8
    .kernarg_segment_size: 456
    .language:       OpenCL C
    .language_version:
      - 2
      - 0
    .max_flat_workgroup_size: 512
    .name:           _Z8mega_fwd6Params
    .private_segment_fixed_size: 0
    .sgpr_count:     106
    .sgpr_spill_count: 130
    .symbol:         _Z8mega_fwd6Params.kd
    .uniform_work_group_size: 1
    .uses_dynamic_stack: false
    .vgpr_count:     256
    .vgpr_spill_count: 0
    .wavefront_size: 64
